# v10 + GEMM loops: drop the back-to-back s_setprio 0 / s_setprio 1 pair in the middle of each 32-MFMA segment
# speedup vs baseline: 1.0017x; 1.0017x over previous
; #define PG8_STAGE(bufoff, gbase, voff) do { _Pragma("unroll") for (int _i = 0; _i < 2; ++_i) \
;         __builtin_amdgcn_global_load_lds((const unsigned*)((const char*)(gbase) + (voff)[_i]), (LAS unsigned*)(lds + (bufoff) + ldsw + _i * 8192), 16, 0, 0); } while (0)
; #define PG8_LDA(dst, b, h) do { _Pragma("unroll") for (int m = 0; m < 4; ++m) _Pragma("unroll") for (int k = 0; k < 2; ++k) dst[m][k] = *(const LAS bf16x8*)(lds + PG8_SA(b, h) + aoff + m * 2048 + k * 1024); } while (0)
; #define PG8_LDB(dst, b, h) do { _Pragma("unroll") for (int n = 0; n < 2; ++n) _Pragma("unroll") for (int k = 0; k < 2; ++k) dst[n][k] = *(const LAS bf16x8*)(lds + PG8_SB(b, h) + boff + n * 2048 + k * 1024); } while (0)
; #define PG8_MMA(ai, bj, At, Bt) do { __builtin_amdgcn_s_setprio(1); _Pragma("unroll") for (int m = 0; m < 4; ++m) _Pragma("unroll") for (int n = 0; n < 2; ++n) _Pragma("unroll") for (int k = 0; k < 2; ++k) \
;         acc[ai][bj][m][n] = __builtin_amdgcn_mfma_f32_16x16x32_bf16(Bt[n][k], At[m][k], acc[ai][bj][m][n], 0, 0, 0); __builtin_amdgcn_s_setprio(0); } while (0)
; #define PG8_WAIT_V(n) asm volatile("s_waitcnt vmcnt(" #n ")" ::: "memory")
; #define PG8_WAIT_L(n) asm volatile("s_waitcnt lgkmcnt(" #n ")" ::: "memory")
; #define PG8_BAR __builtin_amdgcn_s_barrier()
; #define PG8_SCHED __builtin_amdgcn_sched_barrier(0)
; template <class Epi, class Sched>
; __device__ __forceinline__ void gemm_phase(const int tid, LAS unsigned char* lds, const Gemm g, const Sched& S, const Epi& E) {
;     ...
;         for (int t = 0; t < nt; t += 2) {
;             const bool last = (t == nt - 2);
;             const char* a1 = cA + (size_t)(t + 1) * kstepA;
;             const char* a2 = last ? nA : cA + (size_t)(t + 2) * kstepA; const char* b2 = last ? nB : cB + (size_t)(t + 2) * kstepB;
;             const char* a3 = a2 + kstepA; const char* b3 = b2 + kstepB;
;             PG8_LDB(B0, 0, 0); PG8_LDB(B1, 0, 1); PG8_SCHED; PG8_LDA(At, 0, 0); PG8_STAGE(PG8_SA(1, 1), a1 + hstepA, voffA);
;             PG8_WAIT_V(8); PG8_WAIT_L(0); PG8_BAR; PG8_MMA(0, 0, At, B0); PG8_MMA(0, 1, At, B1); PG8_BAR; PG8_SCHED;
;             PG8_LDA(At, 0, 1); PG8_STAGE(PG8_SB(0, 0), b2, voffB); PG8_STAGE(PG8_SB(0, 1), b2 + hstepB, voffB); PG8_STAGE(PG8_SA(0, 0), a2, voffA);
;             PG8_WAIT_V(8); PG8_WAIT_L(0); PG8_BAR; PG8_MMA(1, 0, At, B0); PG8_MMA(1, 1, At, B1); PG8_BAR; PG8_SCHED;
.LBB0_135:
	s_add_u32 s24, s6, 0x4000
	s_addc_u32 s25, s7, 0
	s_cmp_eq_u32 s66, 28
	s_cselect_b32 s28, s19, s24
	s_cselect_b32 s29, s13, s25
	s_cselect_b32 s26, s63, s64
	s_cselect_b32 s27, s17, s65
	s_add_u32 s24, s28, 0x8000
	s_addc_u32 s25, s29, 0
	s_add_i32 s67, 16, 0x10000
	s_add_i32 s78, 16, 0x14000
	s_waitcnt vmcnt(0)
	v_add_u32_e32 v78, s67, v180
	v_add_u32_e32 v178, s78, v180
	ds_read_b128 v[58:61], v78
	ds_read_b128 v[62:65], v78 offset:1024
	ds_read_b128 v[74:77], v78 offset:2048
	ds_read_b128 v[78:81], v78 offset:3072
	ds_read_b128 v[174:177], v178
	ds_read_b128 v[182:185], v178 offset:1024
	ds_read_b128 v[186:189], v178 offset:2048
	ds_read_b128 v[190:193], v178 offset:3072
	s_add_i32 m0, s15, 0xc000
	ds_read_b128 v[208:211], v181
	ds_read_b128 v[212:215], v181 offset:1024
	ds_read_b128 v[216:219], v181 offset:2048
	ds_read_b128 v[220:223], v181 offset:3072
	ds_read_b128 v[236:239], v181 offset:4096
	ds_read_b128 v[244:247], v181 offset:5120
	ds_read_b128 v[248:251], v181 offset:6144
	ds_read_b128 v[204:207], v181 offset:7168
	global_load_lds_dwordx4 v172, s[6:7]
	s_add_i32 m0, s15, 0xe000
	s_nop 0
	global_load_lds_dwordx4 v170, s[6:7]
	s_waitcnt vmcnt(8)
	s_waitcnt lgkmcnt(0)
	s_barrier
	s_setprio 1
	s_waitcnt lgkmcnt(0)
	v_mfma_f32_16x16x32_bf16 v[142:145], v[58:61], v[208:211], v[142:145]
	v_mfma_f32_16x16x32_bf16 v[138:141], v[74:77], v[208:211], v[138:141]
	v_mfma_f32_16x16x32_bf16 v[126:129], v[58:61], v[216:219], v[126:129]
	v_mfma_f32_16x16x32_bf16 v[122:125], v[74:77], v[216:219], v[122:125]
	v_mfma_f32_16x16x32_bf16 v[110:113], v[58:61], v[236:239], v[110:113]
	v_mfma_f32_16x16x32_bf16 v[106:109], v[74:77], v[236:239], v[106:109]
	v_mfma_f32_16x16x32_bf16 v[94:97], v[58:61], v[248:251], v[94:97]
	v_mfma_f32_16x16x32_bf16 v[90:93], v[74:77], v[248:251], v[90:93]
	v_mfma_f32_16x16x32_bf16 v[142:145], v[62:65], v[212:215], v[142:145]
	v_mfma_f32_16x16x32_bf16 v[138:141], v[78:81], v[212:215], v[138:141]
	v_mfma_f32_16x16x32_bf16 v[126:129], v[62:65], v[220:223], v[126:129]
	v_mfma_f32_16x16x32_bf16 v[122:125], v[78:81], v[220:223], v[122:125]
	v_mfma_f32_16x16x32_bf16 v[110:113], v[62:65], v[244:247], v[110:113]
	v_mfma_f32_16x16x32_bf16 v[106:109], v[78:81], v[244:247], v[106:109]
	v_mfma_f32_16x16x32_bf16 v[94:97], v[62:65], v[204:207], v[94:97]
	v_mfma_f32_16x16x32_bf16 v[90:93], v[78:81], v[204:207], v[90:93]
	v_mfma_f32_16x16x32_bf16 v[134:137], v[174:177], v[208:211], v[134:137]
	v_mfma_f32_16x16x32_bf16 v[130:133], v[186:189], v[208:211], v[130:133]
	v_mfma_f32_16x16x32_bf16 v[118:121], v[174:177], v[216:219], v[118:121]
	v_mfma_f32_16x16x32_bf16 v[114:117], v[186:189], v[216:219], v[114:117]
	v_mfma_f32_16x16x32_bf16 v[102:105], v[174:177], v[236:239], v[102:105]
	v_mfma_f32_16x16x32_bf16 v[98:101], v[186:189], v[236:239], v[98:101]
	v_mfma_f32_16x16x32_bf16 v[86:89], v[174:177], v[248:251], v[86:89]
	v_mfma_f32_16x16x32_bf16 v[82:85], v[186:189], v[248:251], v[82:85]
	v_mfma_f32_16x16x32_bf16 v[134:137], v[182:185], v[212:215], v[134:137]
	v_mfma_f32_16x16x32_bf16 v[130:133], v[190:193], v[212:215], v[130:133]
	v_mfma_f32_16x16x32_bf16 v[118:121], v[182:185], v[220:223], v[118:121]
	v_mfma_f32_16x16x32_bf16 v[114:117], v[190:193], v[220:223], v[114:117]
	v_mfma_f32_16x16x32_bf16 v[102:105], v[182:185], v[244:247], v[102:105]
	v_mfma_f32_16x16x32_bf16 v[98:101], v[190:193], v[244:247], v[98:101]
	v_mfma_f32_16x16x32_bf16 v[86:89], v[182:185], v[204:207], v[86:89]
	v_mfma_f32_16x16x32_bf16 v[82:85], v[190:193], v[204:207], v[82:85]
	s_setprio 0
	s_barrier
	s_add_i32 s67, s67, s54
	s_mov_b32 m0, s67
	ds_read_b128 v[204:207], v181 offset:16384
	ds_read_b128 v[208:211], v181 offset:17408
	ds_read_b128 v[212:215], v181 offset:18432
	ds_read_b128 v[216:219], v181 offset:19456
	ds_read_b128 v[220:223], v181 offset:20480
	ds_read_b128 v[236:239], v181 offset:21504
	ds_read_b128 v[244:247], v181 offset:22528
	ds_read_b128 v[248:251], v181 offset:23552
	global_load_lds_dwordx4 v0, s[26:27]
	s_add_i32 m0, s67, 0x2000
	s_add_u32 s76, s26, 0x4000
	s_addc_u32 s77, s27, 0
	s_add_i32 s67, s78, s54
	global_load_lds_dwordx4 v150, s[26:27]
	s_mov_b32 m0, s67
	s_nop 0
	global_load_lds_dwordx4 v0, s[76:77]
	s_add_i32 m0, s67, 0x2000
	s_nop 0
	global_load_lds_dwordx4 v150, s[76:77]
	s_mov_b32 m0, s15
	s_nop 0
	global_load_lds_dwordx4 v146, s[28:29]
	v_lshl_add_u64 v[178:179], s[28:29], 0, v[148:149]
	s_mov_b32 m0, s55
	s_nop 0
	global_load_lds_dwordx4 v[178:179], off
	s_waitcnt vmcnt(8)
	s_waitcnt lgkmcnt(0)
	s_barrier
	s_setprio 1
	s_waitcnt lgkmcnt(0)
	v_mfma_f32_16x16x32_bf16 v[70:73], v[58:61], v[204:207], v[70:73]
	v_mfma_f32_16x16x32_bf16 v[66:69], v[74:77], v[204:207], v[66:69]
	v_mfma_f32_16x16x32_bf16 v[46:49], v[58:61], v[212:215], v[46:49]
	v_mfma_f32_16x16x32_bf16 v[42:45], v[74:77], v[212:215], v[42:45]
	v_mfma_f32_16x16x32_bf16 v[30:33], v[58:61], v[220:223], v[30:33]
	v_mfma_f32_16x16x32_bf16 v[26:29], v[74:77], v[220:223], v[26:29]
	v_mfma_f32_16x16x32_bf16 v[14:17], v[58:61], v[244:247], v[14:17]
	v_mfma_f32_16x16x32_bf16 v[10:13], v[74:77], v[244:247], v[10:13]
	v_mfma_f32_16x16x32_bf16 v[70:73], v[62:65], v[208:211], v[70:73]
	v_mfma_f32_16x16x32_bf16 v[66:69], v[78:81], v[208:211], v[66:69]
	v_mfma_f32_16x16x32_bf16 v[46:49], v[62:65], v[216:219], v[46:49]
	v_mfma_f32_16x16x32_bf16 v[42:45], v[78:81], v[216:219], v[42:45]
	v_mfma_f32_16x16x32_bf16 v[30:33], v[62:65], v[236:239], v[30:33]
	v_mfma_f32_16x16x32_bf16 v[26:29], v[78:81], v[236:239], v[26:29]
	v_mfma_f32_16x16x32_bf16 v[14:17], v[62:65], v[248:251], v[14:17]
	v_mfma_f32_16x16x32_bf16 v[10:13], v[78:81], v[248:251], v[10:13]
	v_mfma_f32_16x16x32_bf16 v[54:57], v[174:177], v[204:207], v[54:57]
	v_mfma_f32_16x16x32_bf16 v[50:53], v[186:189], v[204:207], v[50:53]
	v_mfma_f32_16x16x32_bf16 v[38:41], v[174:177], v[212:215], v[38:41]
	v_mfma_f32_16x16x32_bf16 v[34:37], v[186:189], v[212:215], v[34:37]
	v_mfma_f32_16x16x32_bf16 v[22:25], v[174:177], v[220:223], v[22:25]
	v_mfma_f32_16x16x32_bf16 v[18:21], v[186:189], v[220:223], v[18:21]
	v_mfma_f32_16x16x32_bf16 v[6:9], v[174:177], v[244:247], v[6:9]
	v_mfma_f32_16x16x32_bf16 v[2:5], v[186:189], v[244:247], v[2:5]
	v_mfma_f32_16x16x32_bf16 v[54:57], v[182:185], v[208:211], v[54:57]
	v_mfma_f32_16x16x32_bf16 v[50:53], v[190:193], v[208:211], v[50:53]
	v_mfma_f32_16x16x32_bf16 v[38:41], v[182:185], v[216:219], v[38:41]
	v_mfma_f32_16x16x32_bf16 v[34:37], v[190:193], v[216:219], v[34:37]
	v_mfma_f32_16x16x32_bf16 v[22:25], v[182:185], v[236:239], v[22:25]
	v_mfma_f32_16x16x32_bf16 v[18:21], v[190:193], v[236:239], v[18:21]
	v_mfma_f32_16x16x32_bf16 v[6:9], v[182:185], v[248:251], v[6:9]
	v_mfma_f32_16x16x32_bf16 v[2:5], v[190:193], v[248:251], v[2:5]
	s_setprio 0
	s_barrier
; #define PG8_STAGE(bufoff, gbase, voff) do { _Pragma("unroll") for (int _i = 0; _i < 2; ++_i) \
;         __builtin_amdgcn_global_load_lds((const unsigned*)((const char*)(gbase) + (voff)[_i]), (LAS unsigned*)(lds + (bufoff) + ldsw + _i * 8192), 16, 0, 0); } while (0)
; #define PG8_LDA(dst, b, h) do { _Pragma("unroll") for (int m = 0; m < 4; ++m) _Pragma("unroll") for (int k = 0; k < 2; ++k) dst[m][k] = *(const LAS bf16x8*)(lds + PG8_SA(b, h) + aoff + m * 2048 + k * 1024); } while (0)
; #define PG8_LDB(dst, b, h) do { _Pragma("unroll") for (int n = 0; n < 2; ++n) _Pragma("unroll") for (int k = 0; k < 2; ++k) dst[n][k] = *(const LAS bf16x8*)(lds + PG8_SB(b, h) + boff + n * 2048 + k * 1024); } while (0)
; #define PG8_MMA(ai, bj, At, Bt) do { __builtin_amdgcn_s_setprio(1); _Pragma("unroll") for (int m = 0; m < 4; ++m) _Pragma("unroll") for (int n = 0; n < 2; ++n) _Pragma("unroll") for (int k = 0; k < 2; ++k) \
;         acc[ai][bj][m][n] = __builtin_amdgcn_mfma_f32_16x16x32_bf16(Bt[n][k], At[m][k], acc[ai][bj][m][n], 0, 0, 0); __builtin_amdgcn_s_setprio(0); } while (0)
; #define PG8_WAIT_V(n) asm volatile("s_waitcnt vmcnt(" #n ")" ::: "memory")
; #define PG8_WAIT_L(n) asm volatile("s_waitcnt lgkmcnt(" #n ")" ::: "memory")
; #define PG8_BAR __builtin_amdgcn_s_barrier()
; #define PG8_SCHED __builtin_amdgcn_sched_barrier(0)
; template <class Epi, class Sched>
; __device__ __forceinline__ void gemm_phase(const int tid, LAS unsigned char* lds, const Gemm g, const Sched& S, const Epi& E) {
;     ...
;             PG8_LDB(B0, 1, 0); PG8_LDB(B1, 1, 1); PG8_SCHED; PG8_LDA(At, 1, 0); PG8_STAGE(PG8_SA(0, 1), a2 + hstepA, voffA);
;             PG8_WAIT_V(8); PG8_WAIT_L(0); PG8_BAR; PG8_MMA(0, 0, At, B0); PG8_MMA(0, 1, At, B1); PG8_BAR; PG8_SCHED;
;             PG8_LDA(At, 1, 1); PG8_STAGE(PG8_SB(1, 0), b3, voffB); PG8_STAGE(PG8_SB(1, 1), b3 + hstepB, voffB); PG8_STAGE(PG8_SA(1, 0), a3, voffA);
;             PG8_WAIT_V(8); PG8_WAIT_L(0); PG8_BAR; PG8_MMA(1, 0, At, B0); PG8_MMA(1, 1, At, B1); PG8_BAR; PG8_SCHED;
;         }
;         if (wr == 0) PG8_BAR;
	s_add_i32 s67, 16, 0x18000
	s_add_i32 s76, 16, 0x1c000
	v_add_u32_e32 v78, s67, v180
	v_add_u32_e32 v178, s76, v180
	ds_read_b128 v[58:61], v78
	ds_read_b128 v[62:65], v78 offset:1024
	ds_read_b128 v[74:77], v78 offset:2048
	ds_read_b128 v[78:81], v78 offset:3072
	ds_read_b128 v[174:177], v178
	ds_read_b128 v[182:185], v178 offset:1024
	ds_read_b128 v[186:189], v178 offset:2048
	ds_read_b128 v[190:193], v178 offset:3072
	s_add_u32 s28, s28, 0x4000
	s_addc_u32 s29, s29, 0
	s_mov_b32 m0, s56
	ds_read_b128 v[204:207], v181 offset:32768
	ds_read_b128 v[208:211], v181 offset:33792
	ds_read_b128 v[212:215], v181 offset:34816
	ds_read_b128 v[216:219], v181 offset:35840
	ds_read_b128 v[220:223], v181 offset:36864
	ds_read_b128 v[236:239], v181 offset:37888
	ds_read_b128 v[244:247], v181 offset:38912
	ds_read_b128 v[248:251], v181 offset:39936
	global_load_lds_dwordx4 v146, s[28:29]
	s_mov_b32 m0, s57
	s_nop 0
	global_load_lds_dwordx4 v148, s[28:29]
	s_waitcnt vmcnt(8)
	s_waitcnt lgkmcnt(0)
	s_barrier
	s_setprio 1
	s_waitcnt lgkmcnt(0)
	v_mfma_f32_16x16x32_bf16 v[142:145], v[58:61], v[204:207], v[142:145]
	v_mfma_f32_16x16x32_bf16 v[138:141], v[74:77], v[204:207], v[138:141]
	v_mfma_f32_16x16x32_bf16 v[126:129], v[58:61], v[212:215], v[126:129]
	v_mfma_f32_16x16x32_bf16 v[122:125], v[74:77], v[212:215], v[122:125]
	v_mfma_f32_16x16x32_bf16 v[110:113], v[58:61], v[220:223], v[110:113]
	v_mfma_f32_16x16x32_bf16 v[106:109], v[74:77], v[220:223], v[106:109]
	v_mfma_f32_16x16x32_bf16 v[94:97], v[58:61], v[244:247], v[94:97]
	v_mfma_f32_16x16x32_bf16 v[90:93], v[74:77], v[244:247], v[90:93]
	v_mfma_f32_16x16x32_bf16 v[142:145], v[62:65], v[208:211], v[142:145]
	v_mfma_f32_16x16x32_bf16 v[138:141], v[78:81], v[208:211], v[138:141]
	v_mfma_f32_16x16x32_bf16 v[126:129], v[62:65], v[216:219], v[126:129]
	v_mfma_f32_16x16x32_bf16 v[122:125], v[78:81], v[216:219], v[122:125]
	v_mfma_f32_16x16x32_bf16 v[110:113], v[62:65], v[236:239], v[110:113]
	v_mfma_f32_16x16x32_bf16 v[106:109], v[78:81], v[236:239], v[106:109]
	v_mfma_f32_16x16x32_bf16 v[94:97], v[62:65], v[248:251], v[94:97]
	v_mfma_f32_16x16x32_bf16 v[90:93], v[78:81], v[248:251], v[90:93]
	v_mfma_f32_16x16x32_bf16 v[134:137], v[174:177], v[204:207], v[134:137]
	v_mfma_f32_16x16x32_bf16 v[130:133], v[186:189], v[204:207], v[130:133]
	v_mfma_f32_16x16x32_bf16 v[118:121], v[174:177], v[212:215], v[118:121]
	v_mfma_f32_16x16x32_bf16 v[114:117], v[186:189], v[212:215], v[114:117]
	v_mfma_f32_16x16x32_bf16 v[102:105], v[174:177], v[220:223], v[102:105]
	v_mfma_f32_16x16x32_bf16 v[98:101], v[186:189], v[220:223], v[98:101]
	v_mfma_f32_16x16x32_bf16 v[86:89], v[174:177], v[244:247], v[86:89]
	v_mfma_f32_16x16x32_bf16 v[82:85], v[186:189], v[244:247], v[82:85]
	v_mfma_f32_16x16x32_bf16 v[134:137], v[182:185], v[208:211], v[134:137]
	v_mfma_f32_16x16x32_bf16 v[130:133], v[190:193], v[208:211], v[130:133]
	v_mfma_f32_16x16x32_bf16 v[118:121], v[182:185], v[216:219], v[118:121]
	v_mfma_f32_16x16x32_bf16 v[114:117], v[190:193], v[216:219], v[114:117]
	v_mfma_f32_16x16x32_bf16 v[102:105], v[182:185], v[236:239], v[102:105]
	v_mfma_f32_16x16x32_bf16 v[98:101], v[190:193], v[236:239], v[98:101]
	v_mfma_f32_16x16x32_bf16 v[86:89], v[182:185], v[248:251], v[86:89]
	v_mfma_f32_16x16x32_bf16 v[82:85], v[190:193], v[248:251], v[82:85]
	s_setprio 0
	s_barrier
	s_add_u32 s28, s26, 0x8000
	s_addc_u32 s29, s27, 0
	s_add_i32 s67, s67, s54
	s_mov_b32 m0, s67
	ds_read_b128 v[204:207], v181 offset:49152
	ds_read_b128 v[208:211], v181 offset:50176
	ds_read_b128 v[212:215], v181 offset:51200
	ds_read_b128 v[216:219], v181 offset:52224
	ds_read_b128 v[220:223], v181 offset:53248
	ds_read_b128 v[236:239], v181 offset:54272
	ds_read_b128 v[244:247], v181 offset:55296
	ds_read_b128 v[248:251], v181 offset:56320
	global_load_lds_dwordx4 v0, s[28:29]
	s_add_i32 m0, s67, 0x2000
	s_add_u32 s26, s26, 0xc000
	s_addc_u32 s27, s27, 0
	global_load_lds_dwordx4 v150, s[28:29]
	s_add_i32 s28, s76, s54
	s_mov_b32 m0, s28
	s_nop 0
	global_load_lds_dwordx4 v0, s[26:27]
	s_add_i32 m0, s28, 0x2000
	s_nop 0
	global_load_lds_dwordx4 v150, s[26:27]
	s_mov_b32 m0, s58
	s_nop 0
	global_load_lds_dwordx4 v146, s[24:25]
	v_lshl_add_u64 v[178:179], s[24:25], 0, v[148:149]
	s_mov_b32 m0, s59
	s_nop 0
	global_load_lds_dwordx4 v[178:179], off
	s_waitcnt vmcnt(8)
	s_waitcnt lgkmcnt(0)
	s_barrier
	s_setprio 1
	s_waitcnt lgkmcnt(0)
	v_mfma_f32_16x16x32_bf16 v[70:73], v[58:61], v[204:207], v[70:73]
	v_mfma_f32_16x16x32_bf16 v[66:69], v[74:77], v[204:207], v[66:69]
	v_mfma_f32_16x16x32_bf16 v[46:49], v[58:61], v[212:215], v[46:49]
	v_mfma_f32_16x16x32_bf16 v[42:45], v[74:77], v[212:215], v[42:45]
	v_mfma_f32_16x16x32_bf16 v[30:33], v[58:61], v[220:223], v[30:33]
	v_mfma_f32_16x16x32_bf16 v[26:29], v[74:77], v[220:223], v[26:29]
	v_mfma_f32_16x16x32_bf16 v[14:17], v[58:61], v[244:247], v[14:17]
	v_mfma_f32_16x16x32_bf16 v[10:13], v[74:77], v[244:247], v[10:13]
	v_mfma_f32_16x16x32_bf16 v[70:73], v[62:65], v[208:211], v[70:73]
	v_mfma_f32_16x16x32_bf16 v[66:69], v[78:81], v[208:211], v[66:69]
	v_mfma_f32_16x16x32_bf16 v[46:49], v[62:65], v[216:219], v[46:49]
	v_mfma_f32_16x16x32_bf16 v[42:45], v[78:81], v[216:219], v[42:45]
	v_mfma_f32_16x16x32_bf16 v[30:33], v[62:65], v[236:239], v[30:33]
	v_mfma_f32_16x16x32_bf16 v[26:29], v[78:81], v[236:239], v[26:29]
	v_mfma_f32_16x16x32_bf16 v[14:17], v[62:65], v[248:251], v[14:17]
	v_mfma_f32_16x16x32_bf16 v[10:13], v[78:81], v[248:251], v[10:13]
	v_mfma_f32_16x16x32_bf16 v[54:57], v[174:177], v[204:207], v[54:57]
	v_mfma_f32_16x16x32_bf16 v[50:53], v[186:189], v[204:207], v[50:53]
	v_mfma_f32_16x16x32_bf16 v[38:41], v[174:177], v[212:215], v[38:41]
	v_mfma_f32_16x16x32_bf16 v[34:37], v[186:189], v[212:215], v[34:37]
	v_mfma_f32_16x16x32_bf16 v[22:25], v[174:177], v[220:223], v[22:25]
	v_mfma_f32_16x16x32_bf16 v[18:21], v[186:189], v[220:223], v[18:21]
	v_mfma_f32_16x16x32_bf16 v[6:9], v[174:177], v[244:247], v[6:9]
	v_mfma_f32_16x16x32_bf16 v[2:5], v[186:189], v[244:247], v[2:5]
	v_mfma_f32_16x16x32_bf16 v[54:57], v[182:185], v[208:211], v[54:57]
	v_mfma_f32_16x16x32_bf16 v[50:53], v[190:193], v[208:211], v[50:53]
	v_mfma_f32_16x16x32_bf16 v[38:41], v[182:185], v[216:219], v[38:41]
	v_mfma_f32_16x16x32_bf16 v[34:37], v[190:193], v[216:219], v[34:37]
	v_mfma_f32_16x16x32_bf16 v[22:25], v[182:185], v[236:239], v[22:25]
	v_mfma_f32_16x16x32_bf16 v[18:21], v[190:193], v[236:239], v[18:21]
	v_mfma_f32_16x16x32_bf16 v[6:9], v[182:185], v[248:251], v[6:9]
	v_mfma_f32_16x16x32_bf16 v[2:5], v[190:193], v[248:251], v[2:5]
	s_setprio 0
	s_barrier
	s_add_i32 s66, s66, 2
	s_add_u32 s64, s64, 0x10000
	s_addc_u32 s65, s65, 0
	s_add_u32 s6, s6, 0x10000
	s_addc_u32 s7, s7, 0
	s_cmp_gt_u32 s66, 29
	s_cbranch_scc0 .LBB0_135
	s_and_b64 vcc, exec, s[10:11]
	s_cbranch_vccz .LBB0_138
	s_barrier

; #define PG8_STAGE(bufoff, gbase, voff) do { _Pragma("unroll") for (int _i = 0; _i < 2; ++_i) \
;         __builtin_amdgcn_global_load_lds((const unsigned*)((const char*)(gbase) + (voff)[_i]), (LAS unsigned*)(lds + (bufoff) + ldsw + _i * 8192), 16, 0, 0); } while (0)
; #define PG8_LDA(dst, b, h) do { _Pragma("unroll") for (int m = 0; m < 4; ++m) _Pragma("unroll") for (int k = 0; k < 2; ++k) dst[m][k] = *(const LAS bf16x8*)(lds + PG8_SA(b, h) + aoff + m * 2048 + k * 1024); } while (0)
; #define PG8_LDB(dst, b, h) do { _Pragma("unroll") for (int n = 0; n < 2; ++n) _Pragma("unroll") for (int k = 0; k < 2; ++k) dst[n][k] = *(const LAS bf16x8*)(lds + PG8_SB(b, h) + boff + n * 2048 + k * 1024); } while (0)
; #define PG8_MMA(ai, bj, At, Bt) do { __builtin_amdgcn_s_setprio(1); _Pragma("unroll") for (int m = 0; m < 4; ++m) _Pragma("unroll") for (int n = 0; n < 2; ++n) _Pragma("unroll") for (int k = 0; k < 2; ++k) \
;         acc[ai][bj][m][n] = __builtin_amdgcn_mfma_f32_16x16x32_bf16(Bt[n][k], At[m][k], acc[ai][bj][m][n], 0, 0, 0); __builtin_amdgcn_s_setprio(0); } while (0)
; #define PG8_WAIT_V(n) asm volatile("s_waitcnt vmcnt(" #n ")" ::: "memory")
; #define PG8_WAIT_L(n) asm volatile("s_waitcnt lgkmcnt(" #n ")" ::: "memory")
; #define PG8_BAR __builtin_amdgcn_s_barrier()
; #define PG8_SCHED __builtin_amdgcn_sched_barrier(0)
; template <class Epi, class Sched>
; __device__ __forceinline__ void gemm_phase(const int tid, LAS unsigned char* lds, const Gemm g, const Sched& S, const Epi& E) {
;     ...
;         for (int t = 0; t < nt; t += 2) {
;             const bool last = (t == nt - 2);
;             const char* a1 = cA + (size_t)(t + 1) * kstepA;
;             const char* a2 = last ? nA : cA + (size_t)(t + 2) * kstepA; const char* b2 = last ? nB : cB + (size_t)(t + 2) * kstepB;
;             const char* a3 = a2 + kstepA; const char* b3 = b2 + kstepB;
;             PG8_LDB(B0, 0, 0); PG8_LDB(B1, 0, 1); PG8_SCHED; PG8_LDA(At, 0, 0); PG8_STAGE(PG8_SA(1, 1), a1 + hstepA, voffA);
;             PG8_WAIT_V(8); PG8_WAIT_L(0); PG8_BAR; PG8_MMA(0, 0, At, B0); PG8_MMA(0, 1, At, B1); PG8_BAR; PG8_SCHED;
;             PG8_LDA(At, 0, 1); PG8_STAGE(PG8_SB(0, 0), b2, voffB); PG8_STAGE(PG8_SB(0, 1), b2 + hstepB, voffB); PG8_STAGE(PG8_SA(0, 0), a2, voffA);
;             PG8_WAIT_V(8); PG8_WAIT_L(0); PG8_BAR; PG8_MMA(1, 0, At, B0); PG8_MMA(1, 1, At, B1); PG8_BAR; PG8_SCHED;
.LBB0_404:
	s_add_u32 s18, s6, 0xffe00080
	s_addc_u32 s19, s7, -1
	s_add_i32 s61, 16, 0x10000
	s_cmp_eq_u32 s60, 8
	s_cselect_b32 s21, s13, s19
	s_cselect_b32 s20, s57, s18
	s_cselect_b32 s19, s15, s59
	s_cselect_b32 s18, s14, s58
	s_add_i32 s64, 16, 0x14000
	v_add_u32_e32 v156, s61, v141
	v_add_u32_e32 v172, s64, v141
	ds_read_b128 v[144:147], v156
	ds_read_b128 v[148:151], v156 offset:1024
	ds_read_b128 v[152:155], v156 offset:2048
	ds_read_b128 v[156:159], v156 offset:3072
	ds_read_b128 v[160:163], v172
	ds_read_b128 v[164:167], v172 offset:1024
	ds_read_b128 v[168:171], v172 offset:2048
	ds_read_b128 v[172:175], v172 offset:3072
	s_add_i32 m0, s9, 0xc000
	ds_read_b128 v[176:179], v143
	ds_read_b128 v[180:183], v143 offset:1024
	ds_read_b128 v[184:187], v143 offset:2048
	ds_read_b128 v[188:191], v143 offset:3072
	ds_read_b128 v[204:207], v143 offset:4096
	ds_read_b128 v[208:211], v143 offset:5120
	ds_read_b128 v[212:215], v143 offset:6144
	ds_read_b128 v[216:219], v143 offset:7168
	global_load_lds_dwordx4 v138, s[6:7]
	s_add_i32 m0, s9, 0xe000
	s_nop 0
	global_load_lds_dwordx4 v136, s[6:7]
	s_waitcnt vmcnt(8)
	s_waitcnt lgkmcnt(0)
	s_barrier
	s_setprio 1
	s_waitcnt lgkmcnt(0)
	v_mfma_f32_16x16x32_bf16 v[126:129], v[144:147], v[176:179], v[126:129]
	v_mfma_f32_16x16x32_bf16 v[122:125], v[152:155], v[176:179], v[122:125]
	v_mfma_f32_16x16x32_bf16 v[118:121], v[144:147], v[184:187], v[118:121]
	v_mfma_f32_16x16x32_bf16 v[114:117], v[152:155], v[184:187], v[114:117]
	v_mfma_f32_16x16x32_bf16 v[102:105], v[144:147], v[204:207], v[102:105]
	v_mfma_f32_16x16x32_bf16 v[98:101], v[152:155], v[204:207], v[98:101]
	v_mfma_f32_16x16x32_bf16 v[86:89], v[144:147], v[212:215], v[86:89]
	v_mfma_f32_16x16x32_bf16 v[82:85], v[152:155], v[212:215], v[82:85]
	v_mfma_f32_16x16x32_bf16 v[126:129], v[148:151], v[180:183], v[126:129]
	v_mfma_f32_16x16x32_bf16 v[122:125], v[156:159], v[180:183], v[122:125]
	v_mfma_f32_16x16x32_bf16 v[118:121], v[148:151], v[188:191], v[118:121]
	v_mfma_f32_16x16x32_bf16 v[114:117], v[156:159], v[188:191], v[114:117]
	v_mfma_f32_16x16x32_bf16 v[102:105], v[148:151], v[208:211], v[102:105]
	v_mfma_f32_16x16x32_bf16 v[98:101], v[156:159], v[208:211], v[98:101]
	v_mfma_f32_16x16x32_bf16 v[86:89], v[148:151], v[216:219], v[86:89]
	v_mfma_f32_16x16x32_bf16 v[82:85], v[156:159], v[216:219], v[82:85]
	v_mfma_f32_16x16x32_bf16 v[110:113], v[160:163], v[176:179], v[110:113]
	v_mfma_f32_16x16x32_bf16 v[106:109], v[168:171], v[176:179], v[106:109]
	v_mfma_f32_16x16x32_bf16 v[94:97], v[160:163], v[184:187], v[94:97]
	v_mfma_f32_16x16x32_bf16 v[90:93], v[168:171], v[184:187], v[90:93]
	v_mfma_f32_16x16x32_bf16 v[78:81], v[160:163], v[204:207], v[78:81]
	v_mfma_f32_16x16x32_bf16 v[74:77], v[168:171], v[204:207], v[74:77]
	v_mfma_f32_16x16x32_bf16 v[70:73], v[160:163], v[212:215], v[70:73]
	v_mfma_f32_16x16x32_bf16 v[66:69], v[168:171], v[212:215], v[66:69]
	v_mfma_f32_16x16x32_bf16 v[110:113], v[164:167], v[180:183], v[110:113]
	v_mfma_f32_16x16x32_bf16 v[106:109], v[172:175], v[180:183], v[106:109]
	v_mfma_f32_16x16x32_bf16 v[94:97], v[164:167], v[188:191], v[94:97]
	v_mfma_f32_16x16x32_bf16 v[90:93], v[172:175], v[188:191], v[90:93]
	v_mfma_f32_16x16x32_bf16 v[78:81], v[164:167], v[208:211], v[78:81]
	v_mfma_f32_16x16x32_bf16 v[74:77], v[172:175], v[208:211], v[74:77]
	v_mfma_f32_16x16x32_bf16 v[70:73], v[164:167], v[216:219], v[70:73]
	v_mfma_f32_16x16x32_bf16 v[66:69], v[172:175], v[216:219], v[66:69]
	s_setprio 0
	s_barrier
	s_add_i32 s61, s61, s28
	s_mov_b32 m0, s61
	ds_read_b128 v[176:179], v143 offset:16384
	ds_read_b128 v[180:183], v143 offset:17408
	ds_read_b128 v[184:187], v143 offset:18432
	ds_read_b128 v[188:191], v143 offset:19456
	ds_read_b128 v[204:207], v143 offset:20480
	ds_read_b128 v[208:211], v143 offset:21504
	ds_read_b128 v[212:215], v143 offset:22528
	ds_read_b128 v[216:219], v143 offset:23552
	global_load_lds_dwordx4 v134, s[18:19]
	s_add_i32 m0, s61, 0x2000
	s_add_u32 s62, s18, 0x4000
	s_addc_u32 s63, s19, 0
	s_add_i32 s61, s64, s28
	global_load_lds_dwordx4 v130, s[18:19]
	s_mov_b32 m0, s61
	v_lshl_add_u64 v[220:221], s[20:21], 0, v[132:133]
	global_load_lds_dwordx4 v134, s[62:63]
	s_add_i32 m0, s61, 0x2000
	s_nop 0
	global_load_lds_dwordx4 v130, s[62:63]
	v_lshl_add_u64 v[192:193], s[20:21], 0, v[0:1]
	s_mov_b32 m0, s9
	s_nop 0
	global_load_lds_dwordx4 v[192:193], off
	s_mov_b32 m0, s30
	s_nop 0
	global_load_lds_dwordx4 v[220:221], off
	s_waitcnt vmcnt(8)
	s_waitcnt lgkmcnt(0)
	s_barrier
	s_setprio 1
	s_waitcnt lgkmcnt(0)
	v_mfma_f32_16x16x32_bf16 v[62:65], v[144:147], v[176:179], v[62:65]
	v_mfma_f32_16x16x32_bf16 v[58:61], v[152:155], v[176:179], v[58:61]
	v_mfma_f32_16x16x32_bf16 v[54:57], v[144:147], v[184:187], v[54:57]
	v_mfma_f32_16x16x32_bf16 v[50:53], v[152:155], v[184:187], v[50:53]
	v_mfma_f32_16x16x32_bf16 v[38:41], v[144:147], v[204:207], v[38:41]
	v_mfma_f32_16x16x32_bf16 v[34:37], v[152:155], v[204:207], v[34:37]
	v_mfma_f32_16x16x32_bf16 v[22:25], v[144:147], v[212:215], v[22:25]
	v_mfma_f32_16x16x32_bf16 v[18:21], v[152:155], v[212:215], v[18:21]
	v_mfma_f32_16x16x32_bf16 v[62:65], v[148:151], v[180:183], v[62:65]
	v_mfma_f32_16x16x32_bf16 v[58:61], v[156:159], v[180:183], v[58:61]
	v_mfma_f32_16x16x32_bf16 v[54:57], v[148:151], v[188:191], v[54:57]
	v_mfma_f32_16x16x32_bf16 v[50:53], v[156:159], v[188:191], v[50:53]
	v_mfma_f32_16x16x32_bf16 v[38:41], v[148:151], v[208:211], v[38:41]
	v_mfma_f32_16x16x32_bf16 v[34:37], v[156:159], v[208:211], v[34:37]
	v_mfma_f32_16x16x32_bf16 v[22:25], v[148:151], v[216:219], v[22:25]
	v_mfma_f32_16x16x32_bf16 v[18:21], v[156:159], v[216:219], v[18:21]
	v_mfma_f32_16x16x32_bf16 v[46:49], v[160:163], v[176:179], v[46:49]
	v_mfma_f32_16x16x32_bf16 v[42:45], v[168:171], v[176:179], v[42:45]
	v_mfma_f32_16x16x32_bf16 v[30:33], v[160:163], v[184:187], v[30:33]
	v_mfma_f32_16x16x32_bf16 v[26:29], v[168:171], v[184:187], v[26:29]
	v_mfma_f32_16x16x32_bf16 v[14:17], v[160:163], v[204:207], v[14:17]
	v_mfma_f32_16x16x32_bf16 v[10:13], v[168:171], v[204:207], v[10:13]
	v_mfma_f32_16x16x32_bf16 v[6:9], v[160:163], v[212:215], v[6:9]
	v_mfma_f32_16x16x32_bf16 v[2:5], v[168:171], v[212:215], v[2:5]
	v_mfma_f32_16x16x32_bf16 v[46:49], v[164:167], v[180:183], v[46:49]
	v_mfma_f32_16x16x32_bf16 v[42:45], v[172:175], v[180:183], v[42:45]
	v_mfma_f32_16x16x32_bf16 v[30:33], v[164:167], v[188:191], v[30:33]
	v_mfma_f32_16x16x32_bf16 v[26:29], v[172:175], v[188:191], v[26:29]
	v_mfma_f32_16x16x32_bf16 v[14:17], v[164:167], v[208:211], v[14:17]
	v_mfma_f32_16x16x32_bf16 v[10:13], v[172:175], v[208:211], v[10:13]
	v_mfma_f32_16x16x32_bf16 v[6:9], v[164:167], v[216:219], v[6:9]
	v_mfma_f32_16x16x32_bf16 v[2:5], v[172:175], v[216:219], v[2:5]
	s_setprio 0
	s_barrier
; #define PG8_STAGE(bufoff, gbase, voff) do { _Pragma("unroll") for (int _i = 0; _i < 2; ++_i) \
;         __builtin_amdgcn_global_load_lds((const unsigned*)((const char*)(gbase) + (voff)[_i]), (LAS unsigned*)(lds + (bufoff) + ldsw + _i * 8192), 16, 0, 0); } while (0)
; #define PG8_LDA(dst, b, h) do { _Pragma("unroll") for (int m = 0; m < 4; ++m) _Pragma("unroll") for (int k = 0; k < 2; ++k) dst[m][k] = *(const LAS bf16x8*)(lds + PG8_SA(b, h) + aoff + m * 2048 + k * 1024); } while (0)
; #define PG8_LDB(dst, b, h) do { _Pragma("unroll") for (int n = 0; n < 2; ++n) _Pragma("unroll") for (int k = 0; k < 2; ++k) dst[n][k] = *(const LAS bf16x8*)(lds + PG8_SB(b, h) + boff + n * 2048 + k * 1024); } while (0)
; #define PG8_MMA(ai, bj, At, Bt) do { __builtin_amdgcn_s_setprio(1); _Pragma("unroll") for (int m = 0; m < 4; ++m) _Pragma("unroll") for (int n = 0; n < 2; ++n) _Pragma("unroll") for (int k = 0; k < 2; ++k) \
;         acc[ai][bj][m][n] = __builtin_amdgcn_mfma_f32_16x16x32_bf16(Bt[n][k], At[m][k], acc[ai][bj][m][n], 0, 0, 0); __builtin_amdgcn_s_setprio(0); } while (0)
; #define PG8_WAIT_V(n) asm volatile("s_waitcnt vmcnt(" #n ")" ::: "memory")
; #define PG8_WAIT_L(n) asm volatile("s_waitcnt lgkmcnt(" #n ")" ::: "memory")
; #define PG8_BAR __builtin_amdgcn_s_barrier()
; #define PG8_SCHED __builtin_amdgcn_sched_barrier(0)
; template <class Epi, class Sched>
; __device__ __forceinline__ void gemm_phase(const int tid, LAS unsigned char* lds, const Gemm g, const Sched& S, const Epi& E) {
;     ...
;             PG8_LDB(B0, 1, 0); PG8_LDB(B1, 1, 1); PG8_SCHED; PG8_LDA(At, 1, 0); PG8_STAGE(PG8_SA(0, 1), a2 + hstepA, voffA);
;             PG8_WAIT_V(8); PG8_WAIT_L(0); PG8_BAR; PG8_MMA(0, 0, At, B0); PG8_MMA(0, 1, At, B1); PG8_BAR; PG8_SCHED;
;             PG8_LDA(At, 1, 1); PG8_STAGE(PG8_SB(1, 0), b3, voffB); PG8_STAGE(PG8_SB(1, 1), b3 + hstepB, voffB); PG8_STAGE(PG8_SA(1, 0), a3, voffA);
;             PG8_WAIT_V(8); PG8_WAIT_L(0); PG8_BAR; PG8_MMA(1, 0, At, B0); PG8_MMA(1, 1, At, B1); PG8_BAR; PG8_SCHED;
;         }
;         if (wr == 0) PG8_BAR;
	s_add_i32 s61, 16, 0x18000
	s_add_i32 s62, 16, 0x1c000
	v_add_u32_e32 v156, s61, v141
	v_add_u32_e32 v172, s62, v141
	ds_read_b128 v[144:147], v156
	ds_read_b128 v[148:151], v156 offset:1024
	ds_read_b128 v[152:155], v156 offset:2048
	ds_read_b128 v[156:159], v156 offset:3072
	ds_read_b128 v[160:163], v172
	ds_read_b128 v[164:167], v172 offset:1024
	ds_read_b128 v[168:171], v172 offset:2048
	ds_read_b128 v[172:175], v172 offset:3072
	s_add_u32 s20, s20, 0x200000
	s_addc_u32 s21, s21, 0
	s_mov_b32 m0, s31
	ds_read_b128 v[176:179], v143 offset:32768
	ds_read_b128 v[180:183], v143 offset:33792
	ds_read_b128 v[184:187], v143 offset:34816
	ds_read_b128 v[188:191], v143 offset:35840
	ds_read_b128 v[204:207], v143 offset:36864
	ds_read_b128 v[208:211], v143 offset:37888
	ds_read_b128 v[212:215], v143 offset:38912
	ds_read_b128 v[216:219], v143 offset:39936
	global_load_lds_dwordx4 v0, s[20:21]
	s_mov_b32 m0, s34
	s_nop 0
	global_load_lds_dwordx4 v132, s[20:21]
	s_waitcnt vmcnt(8)
	s_waitcnt lgkmcnt(0)
	s_barrier
	s_setprio 1
	s_waitcnt lgkmcnt(0)
	v_mfma_f32_16x16x32_bf16 v[126:129], v[144:147], v[176:179], v[126:129]
	v_mfma_f32_16x16x32_bf16 v[122:125], v[152:155], v[176:179], v[122:125]
	v_mfma_f32_16x16x32_bf16 v[118:121], v[144:147], v[184:187], v[118:121]
	v_mfma_f32_16x16x32_bf16 v[114:117], v[152:155], v[184:187], v[114:117]
	v_mfma_f32_16x16x32_bf16 v[102:105], v[144:147], v[204:207], v[102:105]
	v_mfma_f32_16x16x32_bf16 v[98:101], v[152:155], v[204:207], v[98:101]
	v_mfma_f32_16x16x32_bf16 v[86:89], v[144:147], v[212:215], v[86:89]
	v_mfma_f32_16x16x32_bf16 v[82:85], v[152:155], v[212:215], v[82:85]
	v_mfma_f32_16x16x32_bf16 v[126:129], v[148:151], v[180:183], v[126:129]
	v_mfma_f32_16x16x32_bf16 v[122:125], v[156:159], v[180:183], v[122:125]
	v_mfma_f32_16x16x32_bf16 v[118:121], v[148:151], v[188:191], v[118:121]
	v_mfma_f32_16x16x32_bf16 v[114:117], v[156:159], v[188:191], v[114:117]
	v_mfma_f32_16x16x32_bf16 v[102:105], v[148:151], v[208:211], v[102:105]
	v_mfma_f32_16x16x32_bf16 v[98:101], v[156:159], v[208:211], v[98:101]
	v_mfma_f32_16x16x32_bf16 v[86:89], v[148:151], v[216:219], v[86:89]
	v_mfma_f32_16x16x32_bf16 v[82:85], v[156:159], v[216:219], v[82:85]
	v_mfma_f32_16x16x32_bf16 v[110:113], v[160:163], v[176:179], v[110:113]
	v_mfma_f32_16x16x32_bf16 v[106:109], v[168:171], v[176:179], v[106:109]
	v_mfma_f32_16x16x32_bf16 v[94:97], v[160:163], v[184:187], v[94:97]
	v_mfma_f32_16x16x32_bf16 v[90:93], v[168:171], v[184:187], v[90:93]
	v_mfma_f32_16x16x32_bf16 v[78:81], v[160:163], v[204:207], v[78:81]
	v_mfma_f32_16x16x32_bf16 v[74:77], v[168:171], v[204:207], v[74:77]
	v_mfma_f32_16x16x32_bf16 v[70:73], v[160:163], v[212:215], v[70:73]
	v_mfma_f32_16x16x32_bf16 v[66:69], v[168:171], v[212:215], v[66:69]
	v_mfma_f32_16x16x32_bf16 v[110:113], v[164:167], v[180:183], v[110:113]
	v_mfma_f32_16x16x32_bf16 v[106:109], v[172:175], v[180:183], v[106:109]
	v_mfma_f32_16x16x32_bf16 v[94:97], v[164:167], v[188:191], v[94:97]
	v_mfma_f32_16x16x32_bf16 v[90:93], v[172:175], v[188:191], v[90:93]
	v_mfma_f32_16x16x32_bf16 v[78:81], v[164:167], v[208:211], v[78:81]
	v_mfma_f32_16x16x32_bf16 v[74:77], v[172:175], v[208:211], v[74:77]
	v_mfma_f32_16x16x32_bf16 v[70:73], v[164:167], v[216:219], v[70:73]
	v_mfma_f32_16x16x32_bf16 v[66:69], v[172:175], v[216:219], v[66:69]
	s_setprio 0
	s_barrier
	s_add_u32 s20, s18, 0x8000
	s_addc_u32 s21, s19, 0
	s_add_i32 s61, s61, s28
	s_mov_b32 m0, s61
	ds_read_b128 v[176:179], v143 offset:49152
	ds_read_b128 v[180:183], v143 offset:50176
	ds_read_b128 v[184:187], v143 offset:51200
	ds_read_b128 v[188:191], v143 offset:52224
	ds_read_b128 v[204:207], v143 offset:53248
	ds_read_b128 v[208:211], v143 offset:54272
	ds_read_b128 v[212:215], v143 offset:55296
	ds_read_b128 v[216:219], v143 offset:56320
	global_load_lds_dwordx4 v134, s[20:21]
	s_add_i32 m0, s61, 0x2000
	s_add_u32 s18, s18, 0xc000
	s_addc_u32 s19, s19, 0
	global_load_lds_dwordx4 v130, s[20:21]
	s_add_i32 s20, s62, s28
	s_mov_b32 m0, s20
	v_lshl_add_u64 v[192:193], v[192:193], 0, s[88:89]
	global_load_lds_dwordx4 v134, s[18:19]
	s_add_i32 m0, s20, 0x2000
	s_nop 0
	global_load_lds_dwordx4 v130, s[18:19]
	s_mov_b32 m0, s35
	s_nop 0
	global_load_lds_dwordx4 v[192:193], off
	v_lshl_add_u64 v[192:193], v[220:221], 0, s[88:89]
	s_mov_b32 m0, s52
	s_nop 0
	global_load_lds_dwordx4 v[192:193], off
	s_waitcnt vmcnt(8)
	s_waitcnt lgkmcnt(0)
	s_barrier
	s_setprio 1
	s_waitcnt lgkmcnt(0)
	v_mfma_f32_16x16x32_bf16 v[62:65], v[144:147], v[176:179], v[62:65]
	v_mfma_f32_16x16x32_bf16 v[58:61], v[152:155], v[176:179], v[58:61]
	v_mfma_f32_16x16x32_bf16 v[54:57], v[144:147], v[184:187], v[54:57]
	v_mfma_f32_16x16x32_bf16 v[50:53], v[152:155], v[184:187], v[50:53]
	v_mfma_f32_16x16x32_bf16 v[38:41], v[144:147], v[204:207], v[38:41]
	v_mfma_f32_16x16x32_bf16 v[34:37], v[152:155], v[204:207], v[34:37]
	v_mfma_f32_16x16x32_bf16 v[22:25], v[144:147], v[212:215], v[22:25]
	v_mfma_f32_16x16x32_bf16 v[18:21], v[152:155], v[212:215], v[18:21]
	v_mfma_f32_16x16x32_bf16 v[62:65], v[148:151], v[180:183], v[62:65]
	v_mfma_f32_16x16x32_bf16 v[58:61], v[156:159], v[180:183], v[58:61]
	v_mfma_f32_16x16x32_bf16 v[54:57], v[148:151], v[188:191], v[54:57]
	v_mfma_f32_16x16x32_bf16 v[50:53], v[156:159], v[188:191], v[50:53]
	v_mfma_f32_16x16x32_bf16 v[38:41], v[148:151], v[208:211], v[38:41]
	v_mfma_f32_16x16x32_bf16 v[34:37], v[156:159], v[208:211], v[34:37]
	v_mfma_f32_16x16x32_bf16 v[22:25], v[148:151], v[216:219], v[22:25]
	v_mfma_f32_16x16x32_bf16 v[18:21], v[156:159], v[216:219], v[18:21]
	v_mfma_f32_16x16x32_bf16 v[46:49], v[160:163], v[176:179], v[46:49]
	v_mfma_f32_16x16x32_bf16 v[42:45], v[168:171], v[176:179], v[42:45]
	v_mfma_f32_16x16x32_bf16 v[30:33], v[160:163], v[184:187], v[30:33]
	v_mfma_f32_16x16x32_bf16 v[26:29], v[168:171], v[184:187], v[26:29]
	v_mfma_f32_16x16x32_bf16 v[14:17], v[160:163], v[204:207], v[14:17]
	v_mfma_f32_16x16x32_bf16 v[10:13], v[168:171], v[204:207], v[10:13]
	v_mfma_f32_16x16x32_bf16 v[6:9], v[160:163], v[212:215], v[6:9]
	v_mfma_f32_16x16x32_bf16 v[2:5], v[168:171], v[212:215], v[2:5]
	v_mfma_f32_16x16x32_bf16 v[46:49], v[164:167], v[180:183], v[46:49]
	v_mfma_f32_16x16x32_bf16 v[42:45], v[172:175], v[180:183], v[42:45]
	v_mfma_f32_16x16x32_bf16 v[30:33], v[164:167], v[188:191], v[30:33]
	v_mfma_f32_16x16x32_bf16 v[26:29], v[172:175], v[188:191], v[26:29]
	v_mfma_f32_16x16x32_bf16 v[14:17], v[164:167], v[208:211], v[14:17]
	v_mfma_f32_16x16x32_bf16 v[10:13], v[172:175], v[208:211], v[10:13]
	v_mfma_f32_16x16x32_bf16 v[6:9], v[164:167], v[216:219], v[6:9]
	v_mfma_f32_16x16x32_bf16 v[2:5], v[172:175], v[216:219], v[2:5]
	s_setprio 0
	s_barrier
	s_add_i32 s60, s60, 2
	s_add_u32 s58, s58, 0x10000
	s_addc_u32 s59, s59, 0
	s_add_u32 s6, s6, 0x100
	s_addc_u32 s7, s7, 0
	s_cmp_gt_u32 s60, 9
	s_cbranch_scc0 .LBB0_404
	s_and_b64 vcc, exec, s[10:11]
	s_cbranch_vccz .LBB0_407
	s_barrier

; #define PG8_STAGE(bufoff, gbase, voff) do { _Pragma("unroll") for (int _i = 0; _i < 2; ++_i) \
;         __builtin_amdgcn_global_load_lds((const unsigned*)((const char*)(gbase) + (voff)[_i]), (LAS unsigned*)(lds + (bufoff) + ldsw + _i * 8192), 16, 0, 0); } while (0)
; #define PG8_LDA(dst, b, h) do { _Pragma("unroll") for (int m = 0; m < 4; ++m) _Pragma("unroll") for (int k = 0; k < 2; ++k) dst[m][k] = *(const LAS bf16x8*)(lds + PG8_SA(b, h) + aoff + m * 2048 + k * 1024); } while (0)
; #define PG8_LDB(dst, b, h) do { _Pragma("unroll") for (int n = 0; n < 2; ++n) _Pragma("unroll") for (int k = 0; k < 2; ++k) dst[n][k] = *(const LAS bf16x8*)(lds + PG8_SB(b, h) + boff + n * 2048 + k * 1024); } while (0)
; #define PG8_MMA(ai, bj, At, Bt) do { __builtin_amdgcn_s_setprio(1); _Pragma("unroll") for (int m = 0; m < 4; ++m) _Pragma("unroll") for (int n = 0; n < 2; ++n) _Pragma("unroll") for (int k = 0; k < 2; ++k) \
;         acc[ai][bj][m][n] = __builtin_amdgcn_mfma_f32_16x16x32_bf16(Bt[n][k], At[m][k], acc[ai][bj][m][n], 0, 0, 0); __builtin_amdgcn_s_setprio(0); } while (0)
; #define PG8_WAIT_V(n) asm volatile("s_waitcnt vmcnt(" #n ")" ::: "memory")
; #define PG8_WAIT_L(n) asm volatile("s_waitcnt lgkmcnt(" #n ")" ::: "memory")
; #define PG8_BAR __builtin_amdgcn_s_barrier()
; #define PG8_SCHED __builtin_amdgcn_sched_barrier(0)
; template <class Epi, class Sched>
; __device__ __forceinline__ void gemm_phase(const int tid, LAS unsigned char* lds, const Gemm g, const Sched& S, const Epi& E) {
;     ...
;         for (int t = 0; t < nt; t += 2) {
;             const bool last = (t == nt - 2);
;             const char* a1 = cA + (size_t)(t + 1) * kstepA;
;             const char* a2 = last ? nA : cA + (size_t)(t + 2) * kstepA; const char* b2 = last ? nB : cB + (size_t)(t + 2) * kstepB;
;             const char* a3 = a2 + kstepA; const char* b3 = b2 + kstepB;
;             PG8_LDB(B0, 0, 0); PG8_LDB(B1, 0, 1); PG8_SCHED; PG8_LDA(At, 0, 0); PG8_STAGE(PG8_SA(1, 1), a1 + hstepA, voffA);
;             PG8_WAIT_V(8); PG8_WAIT_L(0); PG8_BAR; PG8_MMA(0, 0, At, B0); PG8_MMA(0, 1, At, B1); PG8_BAR; PG8_SCHED;
;             PG8_LDA(At, 0, 1); PG8_STAGE(PG8_SB(0, 0), b2, voffB); PG8_STAGE(PG8_SB(0, 1), b2 + hstepB, voffB); PG8_STAGE(PG8_SA(0, 0), a2, voffA);
;             PG8_WAIT_V(8); PG8_WAIT_L(0); PG8_BAR; PG8_MMA(1, 0, At, B0); PG8_MMA(1, 1, At, B1); PG8_BAR; PG8_SCHED;
.LBB0_428:
	s_add_u32 s20, s18, 0xffe00080
	s_addc_u32 s21, s19, -1
	s_add_i32 s63, 16, 0x10000
	s_cmp_eq_u32 s62, 4
	s_cselect_b32 s23, s13, s21
	s_cselect_b32 s22, s58, s20
	s_cselect_b32 s21, s11, s61
	s_cselect_b32 s20, s59, s60
	s_add_i32 s66, 16, 0x14000
	v_add_u32_e32 v156, s63, v141
	v_add_u32_e32 v172, s66, v141
	ds_read_b128 v[144:147], v156
	ds_read_b128 v[148:151], v156 offset:1024
	ds_read_b128 v[152:155], v156 offset:2048
	ds_read_b128 v[156:159], v156 offset:3072
	ds_read_b128 v[160:163], v172
	ds_read_b128 v[164:167], v172 offset:1024
	ds_read_b128 v[168:171], v172 offset:2048
	ds_read_b128 v[172:175], v172 offset:3072
	s_add_i32 m0, s9, 0xc000
	ds_read_b128 v[176:179], v143
	ds_read_b128 v[180:183], v143 offset:1024
	ds_read_b128 v[184:187], v143 offset:2048
	ds_read_b128 v[188:191], v143 offset:3072
	ds_read_b128 v[204:207], v143 offset:4096
	ds_read_b128 v[208:211], v143 offset:5120
	ds_read_b128 v[212:215], v143 offset:6144
	ds_read_b128 v[216:219], v143 offset:7168
	global_load_lds_dwordx4 v138, s[18:19]
	s_add_i32 m0, s9, 0xe000
	s_nop 0
	global_load_lds_dwordx4 v136, s[18:19]
	s_waitcnt vmcnt(8)
	s_waitcnt lgkmcnt(0)
	s_barrier
	s_setprio 1
	s_waitcnt lgkmcnt(0)
	v_mfma_f32_16x16x32_bf16 v[126:129], v[144:147], v[176:179], v[126:129]
	v_mfma_f32_16x16x32_bf16 v[122:125], v[152:155], v[176:179], v[122:125]
	v_mfma_f32_16x16x32_bf16 v[118:121], v[144:147], v[184:187], v[118:121]
	v_mfma_f32_16x16x32_bf16 v[114:117], v[152:155], v[184:187], v[114:117]
	v_mfma_f32_16x16x32_bf16 v[102:105], v[144:147], v[204:207], v[102:105]
	v_mfma_f32_16x16x32_bf16 v[98:101], v[152:155], v[204:207], v[98:101]
	v_mfma_f32_16x16x32_bf16 v[86:89], v[144:147], v[212:215], v[86:89]
	v_mfma_f32_16x16x32_bf16 v[82:85], v[152:155], v[212:215], v[82:85]
	v_mfma_f32_16x16x32_bf16 v[126:129], v[148:151], v[180:183], v[126:129]
	v_mfma_f32_16x16x32_bf16 v[122:125], v[156:159], v[180:183], v[122:125]
	v_mfma_f32_16x16x32_bf16 v[118:121], v[148:151], v[188:191], v[118:121]
	v_mfma_f32_16x16x32_bf16 v[114:117], v[156:159], v[188:191], v[114:117]
	v_mfma_f32_16x16x32_bf16 v[102:105], v[148:151], v[208:211], v[102:105]
	v_mfma_f32_16x16x32_bf16 v[98:101], v[156:159], v[208:211], v[98:101]
	v_mfma_f32_16x16x32_bf16 v[86:89], v[148:151], v[216:219], v[86:89]
	v_mfma_f32_16x16x32_bf16 v[82:85], v[156:159], v[216:219], v[82:85]
	v_mfma_f32_16x16x32_bf16 v[110:113], v[160:163], v[176:179], v[110:113]
	v_mfma_f32_16x16x32_bf16 v[106:109], v[168:171], v[176:179], v[106:109]
	v_mfma_f32_16x16x32_bf16 v[94:97], v[160:163], v[184:187], v[94:97]
	v_mfma_f32_16x16x32_bf16 v[90:93], v[168:171], v[184:187], v[90:93]
	v_mfma_f32_16x16x32_bf16 v[78:81], v[160:163], v[204:207], v[78:81]
	v_mfma_f32_16x16x32_bf16 v[74:77], v[168:171], v[204:207], v[74:77]
	v_mfma_f32_16x16x32_bf16 v[70:73], v[160:163], v[212:215], v[70:73]
	v_mfma_f32_16x16x32_bf16 v[66:69], v[168:171], v[212:215], v[66:69]
	v_mfma_f32_16x16x32_bf16 v[110:113], v[164:167], v[180:183], v[110:113]
	v_mfma_f32_16x16x32_bf16 v[106:109], v[172:175], v[180:183], v[106:109]
	v_mfma_f32_16x16x32_bf16 v[94:97], v[164:167], v[188:191], v[94:97]
	v_mfma_f32_16x16x32_bf16 v[90:93], v[172:175], v[188:191], v[90:93]
	v_mfma_f32_16x16x32_bf16 v[78:81], v[164:167], v[208:211], v[78:81]
	v_mfma_f32_16x16x32_bf16 v[74:77], v[172:175], v[208:211], v[74:77]
	v_mfma_f32_16x16x32_bf16 v[70:73], v[164:167], v[216:219], v[70:73]
	v_mfma_f32_16x16x32_bf16 v[66:69], v[172:175], v[216:219], v[66:69]
	s_setprio 0
	s_barrier
	s_add_i32 s63, s63, s31
	s_mov_b32 m0, s63
	ds_read_b128 v[176:179], v143 offset:16384
	ds_read_b128 v[180:183], v143 offset:17408
	ds_read_b128 v[184:187], v143 offset:18432
	ds_read_b128 v[188:191], v143 offset:19456
	ds_read_b128 v[204:207], v143 offset:20480
	ds_read_b128 v[208:211], v143 offset:21504
	ds_read_b128 v[212:215], v143 offset:22528
	ds_read_b128 v[216:219], v143 offset:23552
	global_load_lds_dwordx4 v130, s[20:21]
	s_add_i32 m0, s63, 0x2000
	s_add_u32 s64, s20, 0x4000
	s_addc_u32 s65, s21, 0
	s_add_i32 s63, s66, s31
	global_load_lds_dwordx4 v134, s[20:21]
	s_mov_b32 m0, s63
	v_lshl_add_u64 v[220:221], s[22:23], 0, v[132:133]
	global_load_lds_dwordx4 v130, s[64:65]
	s_add_i32 m0, s63, 0x2000
	s_nop 0
	global_load_lds_dwordx4 v134, s[64:65]
	v_lshl_add_u64 v[192:193], s[22:23], 0, v[0:1]
	s_mov_b32 m0, s9
	s_nop 0
	global_load_lds_dwordx4 v[192:193], off
	s_mov_b32 m0, s34
	s_nop 0
	global_load_lds_dwordx4 v[220:221], off
	s_waitcnt vmcnt(8)
	s_waitcnt lgkmcnt(0)
	s_barrier
	s_setprio 1
	s_waitcnt lgkmcnt(0)
	v_mfma_f32_16x16x32_bf16 v[62:65], v[144:147], v[176:179], v[62:65]
	v_mfma_f32_16x16x32_bf16 v[58:61], v[152:155], v[176:179], v[58:61]
	v_mfma_f32_16x16x32_bf16 v[54:57], v[144:147], v[184:187], v[54:57]
	v_mfma_f32_16x16x32_bf16 v[50:53], v[152:155], v[184:187], v[50:53]
	v_mfma_f32_16x16x32_bf16 v[38:41], v[144:147], v[204:207], v[38:41]
	v_mfma_f32_16x16x32_bf16 v[34:37], v[152:155], v[204:207], v[34:37]
	v_mfma_f32_16x16x32_bf16 v[22:25], v[144:147], v[212:215], v[22:25]
	v_mfma_f32_16x16x32_bf16 v[18:21], v[152:155], v[212:215], v[18:21]
	v_mfma_f32_16x16x32_bf16 v[62:65], v[148:151], v[180:183], v[62:65]
	v_mfma_f32_16x16x32_bf16 v[58:61], v[156:159], v[180:183], v[58:61]
	v_mfma_f32_16x16x32_bf16 v[54:57], v[148:151], v[188:191], v[54:57]
	v_mfma_f32_16x16x32_bf16 v[50:53], v[156:159], v[188:191], v[50:53]
	v_mfma_f32_16x16x32_bf16 v[38:41], v[148:151], v[208:211], v[38:41]
	v_mfma_f32_16x16x32_bf16 v[34:37], v[156:159], v[208:211], v[34:37]
	v_mfma_f32_16x16x32_bf16 v[22:25], v[148:151], v[216:219], v[22:25]
	v_mfma_f32_16x16x32_bf16 v[18:21], v[156:159], v[216:219], v[18:21]
	v_mfma_f32_16x16x32_bf16 v[46:49], v[160:163], v[176:179], v[46:49]
	v_mfma_f32_16x16x32_bf16 v[42:45], v[168:171], v[176:179], v[42:45]
	v_mfma_f32_16x16x32_bf16 v[30:33], v[160:163], v[184:187], v[30:33]
	v_mfma_f32_16x16x32_bf16 v[26:29], v[168:171], v[184:187], v[26:29]
	v_mfma_f32_16x16x32_bf16 v[14:17], v[160:163], v[204:207], v[14:17]
	v_mfma_f32_16x16x32_bf16 v[10:13], v[168:171], v[204:207], v[10:13]
	v_mfma_f32_16x16x32_bf16 v[6:9], v[160:163], v[212:215], v[6:9]
	v_mfma_f32_16x16x32_bf16 v[2:5], v[168:171], v[212:215], v[2:5]
	v_mfma_f32_16x16x32_bf16 v[46:49], v[164:167], v[180:183], v[46:49]
	v_mfma_f32_16x16x32_bf16 v[42:45], v[172:175], v[180:183], v[42:45]
	v_mfma_f32_16x16x32_bf16 v[30:33], v[164:167], v[188:191], v[30:33]
	v_mfma_f32_16x16x32_bf16 v[26:29], v[172:175], v[188:191], v[26:29]
	v_mfma_f32_16x16x32_bf16 v[14:17], v[164:167], v[208:211], v[14:17]
	v_mfma_f32_16x16x32_bf16 v[10:13], v[172:175], v[208:211], v[10:13]
	v_mfma_f32_16x16x32_bf16 v[6:9], v[164:167], v[216:219], v[6:9]
	v_mfma_f32_16x16x32_bf16 v[2:5], v[172:175], v[216:219], v[2:5]
	s_setprio 0
	s_barrier
; #define PG8_STAGE(bufoff, gbase, voff) do { _Pragma("unroll") for (int _i = 0; _i < 2; ++_i) \
;         __builtin_amdgcn_global_load_lds((const unsigned*)((const char*)(gbase) + (voff)[_i]), (LAS unsigned*)(lds + (bufoff) + ldsw + _i * 8192), 16, 0, 0); } while (0)
; #define PG8_LDA(dst, b, h) do { _Pragma("unroll") for (int m = 0; m < 4; ++m) _Pragma("unroll") for (int k = 0; k < 2; ++k) dst[m][k] = *(const LAS bf16x8*)(lds + PG8_SA(b, h) + aoff + m * 2048 + k * 1024); } while (0)
; #define PG8_LDB(dst, b, h) do { _Pragma("unroll") for (int n = 0; n < 2; ++n) _Pragma("unroll") for (int k = 0; k < 2; ++k) dst[n][k] = *(const LAS bf16x8*)(lds + PG8_SB(b, h) + boff + n * 2048 + k * 1024); } while (0)
; #define PG8_MMA(ai, bj, At, Bt) do { __builtin_amdgcn_s_setprio(1); _Pragma("unroll") for (int m = 0; m < 4; ++m) _Pragma("unroll") for (int n = 0; n < 2; ++n) _Pragma("unroll") for (int k = 0; k < 2; ++k) \
;         acc[ai][bj][m][n] = __builtin_amdgcn_mfma_f32_16x16x32_bf16(Bt[n][k], At[m][k], acc[ai][bj][m][n], 0, 0, 0); __builtin_amdgcn_s_setprio(0); } while (0)
; #define PG8_WAIT_V(n) asm volatile("s_waitcnt vmcnt(" #n ")" ::: "memory")
; #define PG8_WAIT_L(n) asm volatile("s_waitcnt lgkmcnt(" #n ")" ::: "memory")
; #define PG8_BAR __builtin_amdgcn_s_barrier()
; #define PG8_SCHED __builtin_amdgcn_sched_barrier(0)
; template <class Epi, class Sched>
; __device__ __forceinline__ void gemm_phase(const int tid, LAS unsigned char* lds, const Gemm g, const Sched& S, const Epi& E) {
;     ...
;             PG8_LDB(B0, 1, 0); PG8_LDB(B1, 1, 1); PG8_SCHED; PG8_LDA(At, 1, 0); PG8_STAGE(PG8_SA(0, 1), a2 + hstepA, voffA);
;             PG8_WAIT_V(8); PG8_WAIT_L(0); PG8_BAR; PG8_MMA(0, 0, At, B0); PG8_MMA(0, 1, At, B1); PG8_BAR; PG8_SCHED;
;             PG8_LDA(At, 1, 1); PG8_STAGE(PG8_SB(1, 0), b3, voffB); PG8_STAGE(PG8_SB(1, 1), b3 + hstepB, voffB); PG8_STAGE(PG8_SA(1, 0), a3, voffA);
;             PG8_WAIT_V(8); PG8_WAIT_L(0); PG8_BAR; PG8_MMA(1, 0, At, B0); PG8_MMA(1, 1, At, B1); PG8_BAR; PG8_SCHED;
;         }
;         if (wr == 0) PG8_BAR;
	s_add_i32 s63, 16, 0x18000
	s_add_i32 s64, 16, 0x1c000
	v_add_u32_e32 v156, s63, v141
	v_add_u32_e32 v172, s64, v141
	ds_read_b128 v[144:147], v156
	ds_read_b128 v[148:151], v156 offset:1024
	ds_read_b128 v[152:155], v156 offset:2048
	ds_read_b128 v[156:159], v156 offset:3072
	ds_read_b128 v[160:163], v172
	ds_read_b128 v[164:167], v172 offset:1024
	ds_read_b128 v[168:171], v172 offset:2048
	ds_read_b128 v[172:175], v172 offset:3072
	s_add_u32 s22, s22, 0x200000
	s_addc_u32 s23, s23, 0
	s_mov_b32 m0, s35
	ds_read_b128 v[176:179], v143 offset:32768
	ds_read_b128 v[180:183], v143 offset:33792
	ds_read_b128 v[184:187], v143 offset:34816
	ds_read_b128 v[188:191], v143 offset:35840
	ds_read_b128 v[204:207], v143 offset:36864
	ds_read_b128 v[208:211], v143 offset:37888
	ds_read_b128 v[212:215], v143 offset:38912
	ds_read_b128 v[216:219], v143 offset:39936
	global_load_lds_dwordx4 v0, s[22:23]
	s_mov_b32 m0, s52
	s_nop 0
	global_load_lds_dwordx4 v132, s[22:23]
	s_waitcnt vmcnt(8)
	s_waitcnt lgkmcnt(0)
	s_barrier
	s_setprio 1
	s_waitcnt lgkmcnt(0)
	v_mfma_f32_16x16x32_bf16 v[126:129], v[144:147], v[176:179], v[126:129]
	v_mfma_f32_16x16x32_bf16 v[122:125], v[152:155], v[176:179], v[122:125]
	v_mfma_f32_16x16x32_bf16 v[118:121], v[144:147], v[184:187], v[118:121]
	v_mfma_f32_16x16x32_bf16 v[114:117], v[152:155], v[184:187], v[114:117]
	v_mfma_f32_16x16x32_bf16 v[102:105], v[144:147], v[204:207], v[102:105]
	v_mfma_f32_16x16x32_bf16 v[98:101], v[152:155], v[204:207], v[98:101]
	v_mfma_f32_16x16x32_bf16 v[86:89], v[144:147], v[212:215], v[86:89]
	v_mfma_f32_16x16x32_bf16 v[82:85], v[152:155], v[212:215], v[82:85]
	v_mfma_f32_16x16x32_bf16 v[126:129], v[148:151], v[180:183], v[126:129]
	v_mfma_f32_16x16x32_bf16 v[122:125], v[156:159], v[180:183], v[122:125]
	v_mfma_f32_16x16x32_bf16 v[118:121], v[148:151], v[188:191], v[118:121]
	v_mfma_f32_16x16x32_bf16 v[114:117], v[156:159], v[188:191], v[114:117]
	v_mfma_f32_16x16x32_bf16 v[102:105], v[148:151], v[208:211], v[102:105]
	v_mfma_f32_16x16x32_bf16 v[98:101], v[156:159], v[208:211], v[98:101]
	v_mfma_f32_16x16x32_bf16 v[86:89], v[148:151], v[216:219], v[86:89]
	v_mfma_f32_16x16x32_bf16 v[82:85], v[156:159], v[216:219], v[82:85]
	v_mfma_f32_16x16x32_bf16 v[110:113], v[160:163], v[176:179], v[110:113]
	v_mfma_f32_16x16x32_bf16 v[106:109], v[168:171], v[176:179], v[106:109]
	v_mfma_f32_16x16x32_bf16 v[94:97], v[160:163], v[184:187], v[94:97]
	v_mfma_f32_16x16x32_bf16 v[90:93], v[168:171], v[184:187], v[90:93]
	v_mfma_f32_16x16x32_bf16 v[78:81], v[160:163], v[204:207], v[78:81]
	v_mfma_f32_16x16x32_bf16 v[74:77], v[168:171], v[204:207], v[74:77]
	v_mfma_f32_16x16x32_bf16 v[70:73], v[160:163], v[212:215], v[70:73]
	v_mfma_f32_16x16x32_bf16 v[66:69], v[168:171], v[212:215], v[66:69]
	v_mfma_f32_16x16x32_bf16 v[110:113], v[164:167], v[180:183], v[110:113]
	v_mfma_f32_16x16x32_bf16 v[106:109], v[172:175], v[180:183], v[106:109]
	v_mfma_f32_16x16x32_bf16 v[94:97], v[164:167], v[188:191], v[94:97]
	v_mfma_f32_16x16x32_bf16 v[90:93], v[172:175], v[188:191], v[90:93]
	v_mfma_f32_16x16x32_bf16 v[78:81], v[164:167], v[208:211], v[78:81]
	v_mfma_f32_16x16x32_bf16 v[74:77], v[172:175], v[208:211], v[74:77]
	v_mfma_f32_16x16x32_bf16 v[70:73], v[164:167], v[216:219], v[70:73]
	v_mfma_f32_16x16x32_bf16 v[66:69], v[172:175], v[216:219], v[66:69]
	s_setprio 0
	s_barrier
	s_add_u32 s22, s20, 0x8000
	s_addc_u32 s23, s21, 0
	s_add_i32 s63, s63, s31
	s_mov_b32 m0, s63
	ds_read_b128 v[176:179], v143 offset:49152
	ds_read_b128 v[180:183], v143 offset:50176
	ds_read_b128 v[184:187], v143 offset:51200
	ds_read_b128 v[188:191], v143 offset:52224
	ds_read_b128 v[204:207], v143 offset:53248
	ds_read_b128 v[208:211], v143 offset:54272
	ds_read_b128 v[212:215], v143 offset:55296
	ds_read_b128 v[216:219], v143 offset:56320
	global_load_lds_dwordx4 v130, s[22:23]
	s_add_i32 m0, s63, 0x2000
	s_add_u32 s20, s20, 0xc000
	s_addc_u32 s21, s21, 0
	global_load_lds_dwordx4 v134, s[22:23]
	s_add_i32 s22, s64, s31
	s_mov_b32 m0, s22
	v_lshl_add_u64 v[192:193], v[192:193], 0, s[88:89]
	global_load_lds_dwordx4 v130, s[20:21]
	s_add_i32 m0, s22, 0x2000
	s_nop 0
	global_load_lds_dwordx4 v134, s[20:21]
	s_mov_b32 m0, s53
	s_nop 0
	global_load_lds_dwordx4 v[192:193], off
	v_lshl_add_u64 v[192:193], v[220:221], 0, s[88:89]
	s_mov_b32 m0, s54
	s_nop 0
	global_load_lds_dwordx4 v[192:193], off
	s_waitcnt vmcnt(8)
	s_waitcnt lgkmcnt(0)
	s_barrier
	s_setprio 1
	s_waitcnt lgkmcnt(0)
	v_mfma_f32_16x16x32_bf16 v[62:65], v[144:147], v[176:179], v[62:65]
	v_mfma_f32_16x16x32_bf16 v[58:61], v[152:155], v[176:179], v[58:61]
	v_mfma_f32_16x16x32_bf16 v[54:57], v[144:147], v[184:187], v[54:57]
	v_mfma_f32_16x16x32_bf16 v[50:53], v[152:155], v[184:187], v[50:53]
	v_mfma_f32_16x16x32_bf16 v[38:41], v[144:147], v[204:207], v[38:41]
	v_mfma_f32_16x16x32_bf16 v[34:37], v[152:155], v[204:207], v[34:37]
	v_mfma_f32_16x16x32_bf16 v[22:25], v[144:147], v[212:215], v[22:25]
	v_mfma_f32_16x16x32_bf16 v[18:21], v[152:155], v[212:215], v[18:21]
	v_mfma_f32_16x16x32_bf16 v[62:65], v[148:151], v[180:183], v[62:65]
	v_mfma_f32_16x16x32_bf16 v[58:61], v[156:159], v[180:183], v[58:61]
	v_mfma_f32_16x16x32_bf16 v[54:57], v[148:151], v[188:191], v[54:57]
	v_mfma_f32_16x16x32_bf16 v[50:53], v[156:159], v[188:191], v[50:53]
	v_mfma_f32_16x16x32_bf16 v[38:41], v[148:151], v[208:211], v[38:41]
	v_mfma_f32_16x16x32_bf16 v[34:37], v[156:159], v[208:211], v[34:37]
	v_mfma_f32_16x16x32_bf16 v[22:25], v[148:151], v[216:219], v[22:25]
	v_mfma_f32_16x16x32_bf16 v[18:21], v[156:159], v[216:219], v[18:21]
	v_mfma_f32_16x16x32_bf16 v[46:49], v[160:163], v[176:179], v[46:49]
	v_mfma_f32_16x16x32_bf16 v[42:45], v[168:171], v[176:179], v[42:45]
	v_mfma_f32_16x16x32_bf16 v[30:33], v[160:163], v[184:187], v[30:33]
	v_mfma_f32_16x16x32_bf16 v[26:29], v[168:171], v[184:187], v[26:29]
	v_mfma_f32_16x16x32_bf16 v[14:17], v[160:163], v[204:207], v[14:17]
	v_mfma_f32_16x16x32_bf16 v[10:13], v[168:171], v[204:207], v[10:13]
	v_mfma_f32_16x16x32_bf16 v[6:9], v[160:163], v[212:215], v[6:9]
	v_mfma_f32_16x16x32_bf16 v[2:5], v[168:171], v[212:215], v[2:5]
	v_mfma_f32_16x16x32_bf16 v[46:49], v[164:167], v[180:183], v[46:49]
	v_mfma_f32_16x16x32_bf16 v[42:45], v[172:175], v[180:183], v[42:45]
	v_mfma_f32_16x16x32_bf16 v[30:33], v[164:167], v[188:191], v[30:33]
	v_mfma_f32_16x16x32_bf16 v[26:29], v[172:175], v[188:191], v[26:29]
	v_mfma_f32_16x16x32_bf16 v[14:17], v[164:167], v[208:211], v[14:17]
	v_mfma_f32_16x16x32_bf16 v[10:13], v[172:175], v[208:211], v[10:13]
	v_mfma_f32_16x16x32_bf16 v[6:9], v[164:167], v[216:219], v[6:9]
	v_mfma_f32_16x16x32_bf16 v[2:5], v[172:175], v[216:219], v[2:5]
	s_setprio 0
	s_barrier
	s_add_i32 s62, s62, 2
	s_add_u32 s60, s60, 0x10000
	s_addc_u32 s61, s61, 0
	s_add_u32 s18, s18, 0x100
	s_addc_u32 s19, s19, 0
	s_cmp_gt_u32 s62, 5
	s_cbranch_scc0 .LBB0_428
	s_and_b64 vcc, exec, s[6:7]
	s_cbranch_vccz .LBB0_431
	s_barrier

; #define PG8_STAGE(bufoff, gbase, voff) do { _Pragma("unroll") for (int _i = 0; _i < 2; ++_i) \
;         __builtin_amdgcn_global_load_lds((const unsigned*)((const char*)(gbase) + (voff)[_i]), (LAS unsigned*)(lds + (bufoff) + ldsw + _i * 8192), 16, 0, 0); } while (0)
; #define PG8_LDA(dst, b, h) do { _Pragma("unroll") for (int m = 0; m < 4; ++m) _Pragma("unroll") for (int k = 0; k < 2; ++k) dst[m][k] = *(const LAS bf16x8*)(lds + PG8_SA(b, h) + aoff + m * 2048 + k * 1024); } while (0)
; #define PG8_LDB(dst, b, h) do { _Pragma("unroll") for (int n = 0; n < 2; ++n) _Pragma("unroll") for (int k = 0; k < 2; ++k) dst[n][k] = *(const LAS bf16x8*)(lds + PG8_SB(b, h) + boff + n * 2048 + k * 1024); } while (0)
; #define PG8_MMA(ai, bj, At, Bt) do { __builtin_amdgcn_s_setprio(1); _Pragma("unroll") for (int m = 0; m < 4; ++m) _Pragma("unroll") for (int n = 0; n < 2; ++n) _Pragma("unroll") for (int k = 0; k < 2; ++k) \
;         acc[ai][bj][m][n] = __builtin_amdgcn_mfma_f32_16x16x32_bf16(Bt[n][k], At[m][k], acc[ai][bj][m][n], 0, 0, 0); __builtin_amdgcn_s_setprio(0); } while (0)
; #define PG8_WAIT_V(n) asm volatile("s_waitcnt vmcnt(" #n ")" ::: "memory")
; #define PG8_WAIT_L(n) asm volatile("s_waitcnt lgkmcnt(" #n ")" ::: "memory")
; #define PG8_BAR __builtin_amdgcn_s_barrier()
; #define PG8_SCHED __builtin_amdgcn_sched_barrier(0)
; template <class Epi, class Sched>
; __device__ __forceinline__ void gemm_phase(const int tid, LAS unsigned char* lds, const Gemm g, const Sched& S, const Epi& E) {
;     ...
;         for (int t = 0; t < nt; t += 2) {
;             const bool last = (t == nt - 2);
;             const char* a1 = cA + (size_t)(t + 1) * kstepA;
;             const char* a2 = last ? nA : cA + (size_t)(t + 2) * kstepA; const char* b2 = last ? nB : cB + (size_t)(t + 2) * kstepB;
;             const char* a3 = a2 + kstepA; const char* b3 = b2 + kstepB;
;             PG8_LDB(B0, 0, 0); PG8_LDB(B1, 0, 1); PG8_SCHED; PG8_LDA(At, 0, 0); PG8_STAGE(PG8_SA(1, 1), a1 + hstepA, voffA);
;             PG8_WAIT_V(8); PG8_WAIT_L(0); PG8_BAR; PG8_MMA(0, 0, At, B0); PG8_MMA(0, 1, At, B1); PG8_BAR; PG8_SCHED;
;             PG8_LDA(At, 0, 1); PG8_STAGE(PG8_SB(0, 0), b2, voffB); PG8_STAGE(PG8_SB(0, 1), b2 + hstepB, voffB); PG8_STAGE(PG8_SA(0, 0), a2, voffA);
;             PG8_WAIT_V(8); PG8_WAIT_L(0); PG8_BAR; PG8_MMA(1, 0, At, B0); PG8_MMA(1, 1, At, B1); PG8_BAR; PG8_SCHED;
.LBB0_887:
	s_add_u32 s20, s18, 0xfffc0080
	s_addc_u32 s21, s19, -1
	s_add_i32 s36, 16, 0x10000
	s_cmp_eq_u32 s65, 12
	s_cselect_b32 s23, s9, s21
	s_cselect_b32 s22, s61, s20
	v_add_u32_e32 v0, s36, v236
	s_cselect_b32 s21, s11, s64
	s_cselect_b32 s20, s62, s63
	s_add_i32 s37, 16, 0x14000
	ds_read_b128 v[130:133], v0
	ds_read_b128 v[134:137], v0 offset:1024
	ds_read_b128 v[138:141], v0 offset:2048
	ds_read_b128 v[142:145], v0 offset:3072
	v_add_u32_e32 v0, s37, v236
	ds_read_b128 v[146:149], v0
	ds_read_b128 v[150:153], v0 offset:1024
	ds_read_b128 v[154:157], v0 offset:2048
	ds_read_b128 v[158:161], v0 offset:3072
	s_add_i32 m0, s34, 0xc000
	ds_read_b128 v[162:165], v237
	ds_read_b128 v[166:169], v237 offset:1024
	ds_read_b128 v[170:173], v237 offset:2048
	ds_read_b128 v[174:177], v237 offset:3072
	ds_read_b128 v[178:181], v237 offset:4096
	ds_read_b128 v[182:185], v237 offset:5120
	ds_read_b128 v[186:189], v237 offset:6144
	ds_read_b128 v[190:193], v237 offset:7168
	global_load_lds_dwordx4 v218, s[18:19]
	s_add_i32 m0, s34, 0xe000
	s_nop 0
	global_load_lds_dwordx4 v216, s[18:19]
	s_waitcnt vmcnt(8)
	s_waitcnt lgkmcnt(0)
	s_barrier
	s_setprio 1
	s_waitcnt lgkmcnt(0)
	v_mfma_f32_16x16x32_bf16 v[126:129], v[130:133], v[162:165], v[126:129]
	v_mfma_f32_16x16x32_bf16 v[122:125], v[138:141], v[162:165], v[122:125]
	v_mfma_f32_16x16x32_bf16 v[110:113], v[130:133], v[170:173], v[110:113]
	v_mfma_f32_16x16x32_bf16 v[106:109], v[138:141], v[170:173], v[106:109]
	v_mfma_f32_16x16x32_bf16 v[98:101], v[130:133], v[178:181], v[98:101]
	v_mfma_f32_16x16x32_bf16 v[90:93], v[138:141], v[178:181], v[90:93]
	v_mfma_f32_16x16x32_bf16 v[78:81], v[130:133], v[186:189], v[78:81]
	v_mfma_f32_16x16x32_bf16 v[74:77], v[138:141], v[186:189], v[74:77]
	v_mfma_f32_16x16x32_bf16 v[126:129], v[134:137], v[166:169], v[126:129]
	v_mfma_f32_16x16x32_bf16 v[122:125], v[142:145], v[166:169], v[122:125]
	v_mfma_f32_16x16x32_bf16 v[110:113], v[134:137], v[174:177], v[110:113]
	v_mfma_f32_16x16x32_bf16 v[106:109], v[142:145], v[174:177], v[106:109]
	v_mfma_f32_16x16x32_bf16 v[98:101], v[134:137], v[182:185], v[98:101]
	v_mfma_f32_16x16x32_bf16 v[90:93], v[142:145], v[182:185], v[90:93]
	v_mfma_f32_16x16x32_bf16 v[78:81], v[134:137], v[190:193], v[78:81]
	v_mfma_f32_16x16x32_bf16 v[74:77], v[142:145], v[190:193], v[74:77]
	v_mfma_f32_16x16x32_bf16 v[118:121], v[146:149], v[162:165], v[118:121]
	v_mfma_f32_16x16x32_bf16 v[114:117], v[154:157], v[162:165], v[114:117]
	v_mfma_f32_16x16x32_bf16 v[102:105], v[146:149], v[170:173], v[102:105]
	v_mfma_f32_16x16x32_bf16 v[94:97], v[154:157], v[170:173], v[94:97]
	v_mfma_f32_16x16x32_bf16 v[86:89], v[146:149], v[178:181], v[86:89]
	v_mfma_f32_16x16x32_bf16 v[82:85], v[154:157], v[178:181], v[82:85]
	v_mfma_f32_16x16x32_bf16 v[70:73], v[146:149], v[186:189], v[70:73]
	v_mfma_f32_16x16x32_bf16 v[66:69], v[154:157], v[186:189], v[66:69]
	v_mfma_f32_16x16x32_bf16 v[118:121], v[150:153], v[166:169], v[118:121]
	v_mfma_f32_16x16x32_bf16 v[114:117], v[158:161], v[166:169], v[114:117]
	v_mfma_f32_16x16x32_bf16 v[102:105], v[150:153], v[174:177], v[102:105]
	v_mfma_f32_16x16x32_bf16 v[94:97], v[158:161], v[174:177], v[94:97]
	v_mfma_f32_16x16x32_bf16 v[86:89], v[150:153], v[182:185], v[86:89]
	v_mfma_f32_16x16x32_bf16 v[82:85], v[158:161], v[182:185], v[82:85]
	v_mfma_f32_16x16x32_bf16 v[70:73], v[150:153], v[190:193], v[70:73]
	v_mfma_f32_16x16x32_bf16 v[66:69], v[158:161], v[190:193], v[66:69]
	s_setprio 0
	s_barrier
	s_add_i32 s36, s36, s31
	s_mov_b32 m0, s36
	ds_read_b128 v[162:165], v237 offset:16384
	ds_read_b128 v[166:169], v237 offset:17408
	ds_read_b128 v[170:173], v237 offset:18432
	ds_read_b128 v[174:177], v237 offset:19456
	ds_read_b128 v[178:181], v237 offset:20480
	ds_read_b128 v[182:185], v237 offset:21504
	ds_read_b128 v[186:189], v237 offset:22528
	ds_read_b128 v[190:193], v237 offset:23552
	global_load_lds_dwordx4 v210, s[20:21]
	s_add_i32 m0, s36, 0x2000
	s_add_u32 s66, s20, 0x4000
	s_addc_u32 s67, s21, 0
	s_add_i32 s36, s37, s31
	global_load_lds_dwordx4 v214, s[20:21]
	s_mov_b32 m0, s36
	v_lshl_add_u64 v[206:207], s[22:23], 0, v[212:213]
	global_load_lds_dwordx4 v210, s[66:67]
	s_add_i32 m0, s36, 0x2000
	s_nop 0
	global_load_lds_dwordx4 v214, s[66:67]
	v_lshl_add_u64 v[204:205], s[22:23], 0, v[208:209]
	s_mov_b32 m0, s34
	s_nop 0
	global_load_lds_dwordx4 v[204:205], off
	s_mov_b32 m0, s35
	s_nop 0
	global_load_lds_dwordx4 v[206:207], off
	s_waitcnt vmcnt(8)
	s_waitcnt lgkmcnt(0)
	s_barrier
	s_setprio 1
	s_waitcnt lgkmcnt(0)
	v_mfma_f32_16x16x32_bf16 v[62:65], v[130:133], v[162:165], v[62:65]
	v_mfma_f32_16x16x32_bf16 v[58:61], v[138:141], v[162:165], v[58:61]
	v_mfma_f32_16x16x32_bf16 v[46:49], v[130:133], v[170:173], v[46:49]
	v_mfma_f32_16x16x32_bf16 v[42:45], v[138:141], v[170:173], v[42:45]
	v_mfma_f32_16x16x32_bf16 v[34:37], v[130:133], v[178:181], v[34:37]
	v_mfma_f32_16x16x32_bf16 v[26:29], v[138:141], v[178:181], v[26:29]
	v_mfma_f32_16x16x32_bf16 v[14:17], v[130:133], v[186:189], v[14:17]
	v_mfma_f32_16x16x32_bf16 v[10:13], v[138:141], v[186:189], v[10:13]
	v_mfma_f32_16x16x32_bf16 v[62:65], v[134:137], v[166:169], v[62:65]
	v_mfma_f32_16x16x32_bf16 v[58:61], v[142:145], v[166:169], v[58:61]
	v_mfma_f32_16x16x32_bf16 v[46:49], v[134:137], v[174:177], v[46:49]
	v_mfma_f32_16x16x32_bf16 v[42:45], v[142:145], v[174:177], v[42:45]
	v_mfma_f32_16x16x32_bf16 v[34:37], v[134:137], v[182:185], v[34:37]
	v_mfma_f32_16x16x32_bf16 v[26:29], v[142:145], v[182:185], v[26:29]
	v_mfma_f32_16x16x32_bf16 v[14:17], v[134:137], v[190:193], v[14:17]
	v_mfma_f32_16x16x32_bf16 v[10:13], v[142:145], v[190:193], v[10:13]
	v_mfma_f32_16x16x32_bf16 v[54:57], v[146:149], v[162:165], v[54:57]
	v_mfma_f32_16x16x32_bf16 v[50:53], v[154:157], v[162:165], v[50:53]
	v_mfma_f32_16x16x32_bf16 v[38:41], v[146:149], v[170:173], v[38:41]
	v_mfma_f32_16x16x32_bf16 v[30:33], v[154:157], v[170:173], v[30:33]
	v_mfma_f32_16x16x32_bf16 v[22:25], v[146:149], v[178:181], v[22:25]
	v_mfma_f32_16x16x32_bf16 v[18:21], v[154:157], v[178:181], v[18:21]
	v_mfma_f32_16x16x32_bf16 v[6:9], v[146:149], v[186:189], v[6:9]
	v_mfma_f32_16x16x32_bf16 v[2:5], v[154:157], v[186:189], v[2:5]
	v_mfma_f32_16x16x32_bf16 v[54:57], v[150:153], v[166:169], v[54:57]
	v_mfma_f32_16x16x32_bf16 v[50:53], v[158:161], v[166:169], v[50:53]
	v_mfma_f32_16x16x32_bf16 v[38:41], v[150:153], v[174:177], v[38:41]
	v_mfma_f32_16x16x32_bf16 v[30:33], v[158:161], v[174:177], v[30:33]
	v_mfma_f32_16x16x32_bf16 v[22:25], v[150:153], v[182:185], v[22:25]
	v_mfma_f32_16x16x32_bf16 v[18:21], v[158:161], v[182:185], v[18:21]
	v_mfma_f32_16x16x32_bf16 v[6:9], v[150:153], v[190:193], v[6:9]
	v_mfma_f32_16x16x32_bf16 v[2:5], v[158:161], v[190:193], v[2:5]
	s_setprio 0
	s_barrier
; #define PG8_STAGE(bufoff, gbase, voff) do { _Pragma("unroll") for (int _i = 0; _i < 2; ++_i) \
;         __builtin_amdgcn_global_load_lds((const unsigned*)((const char*)(gbase) + (voff)[_i]), (LAS unsigned*)(lds + (bufoff) + ldsw + _i * 8192), 16, 0, 0); } while (0)
; #define PG8_LDA(dst, b, h) do { _Pragma("unroll") for (int m = 0; m < 4; ++m) _Pragma("unroll") for (int k = 0; k < 2; ++k) dst[m][k] = *(const LAS bf16x8*)(lds + PG8_SA(b, h) + aoff + m * 2048 + k * 1024); } while (0)
; #define PG8_LDB(dst, b, h) do { _Pragma("unroll") for (int n = 0; n < 2; ++n) _Pragma("unroll") for (int k = 0; k < 2; ++k) dst[n][k] = *(const LAS bf16x8*)(lds + PG8_SB(b, h) + boff + n * 2048 + k * 1024); } while (0)
; #define PG8_MMA(ai, bj, At, Bt) do { __builtin_amdgcn_s_setprio(1); _Pragma("unroll") for (int m = 0; m < 4; ++m) _Pragma("unroll") for (int n = 0; n < 2; ++n) _Pragma("unroll") for (int k = 0; k < 2; ++k) \
;         acc[ai][bj][m][n] = __builtin_amdgcn_mfma_f32_16x16x32_bf16(Bt[n][k], At[m][k], acc[ai][bj][m][n], 0, 0, 0); __builtin_amdgcn_s_setprio(0); } while (0)
; #define PG8_WAIT_V(n) asm volatile("s_waitcnt vmcnt(" #n ")" ::: "memory")
; #define PG8_WAIT_L(n) asm volatile("s_waitcnt lgkmcnt(" #n ")" ::: "memory")
; #define PG8_BAR __builtin_amdgcn_s_barrier()
; #define PG8_SCHED __builtin_amdgcn_sched_barrier(0)
; template <class Epi, class Sched>
; __device__ __forceinline__ void gemm_phase(const int tid, LAS unsigned char* lds, const Gemm g, const Sched& S, const Epi& E) {
;     ...
;             PG8_LDB(B0, 1, 0); PG8_LDB(B1, 1, 1); PG8_SCHED; PG8_LDA(At, 1, 0); PG8_STAGE(PG8_SA(0, 1), a2 + hstepA, voffA);
;             PG8_WAIT_V(8); PG8_WAIT_L(0); PG8_BAR; PG8_MMA(0, 0, At, B0); PG8_MMA(0, 1, At, B1); PG8_BAR; PG8_SCHED;
;             PG8_LDA(At, 1, 1); PG8_STAGE(PG8_SB(1, 0), b3, voffB); PG8_STAGE(PG8_SB(1, 1), b3 + hstepB, voffB); PG8_STAGE(PG8_SA(1, 0), a3, voffA);
;             PG8_WAIT_V(8); PG8_WAIT_L(0); PG8_BAR; PG8_MMA(1, 0, At, B0); PG8_MMA(1, 1, At, B1); PG8_BAR; PG8_SCHED;
;         }
;         if (wr == 0) PG8_BAR;
	s_add_i32 s36, 16, 0x18000
	v_add_u32_e32 v0, s36, v236
	s_add_i32 s37, 16, 0x1c000
	ds_read_b128 v[130:133], v0
	ds_read_b128 v[134:137], v0 offset:1024
	ds_read_b128 v[138:141], v0 offset:2048
	ds_read_b128 v[142:145], v0 offset:3072
	v_add_u32_e32 v0, s37, v236
	ds_read_b128 v[146:149], v0
	ds_read_b128 v[150:153], v0 offset:1024
	ds_read_b128 v[154:157], v0 offset:2048
	ds_read_b128 v[158:161], v0 offset:3072
	s_add_u32 s22, s22, 0x40000
	s_addc_u32 s23, s23, 0
	s_mov_b32 m0, s52
	ds_read_b128 v[162:165], v237 offset:32768
	ds_read_b128 v[166:169], v237 offset:33792
	ds_read_b128 v[170:173], v237 offset:34816
	ds_read_b128 v[174:177], v237 offset:35840
	ds_read_b128 v[178:181], v237 offset:36864
	ds_read_b128 v[182:185], v237 offset:37888
	ds_read_b128 v[186:189], v237 offset:38912
	ds_read_b128 v[190:193], v237 offset:39936
	global_load_lds_dwordx4 v208, s[22:23]
	s_mov_b32 m0, s53
	s_nop 0
	global_load_lds_dwordx4 v212, s[22:23]
	s_waitcnt vmcnt(8)
	s_waitcnt lgkmcnt(0)
	s_barrier
	s_setprio 1
	s_waitcnt lgkmcnt(0)
	v_mfma_f32_16x16x32_bf16 v[126:129], v[130:133], v[162:165], v[126:129]
	v_mfma_f32_16x16x32_bf16 v[122:125], v[138:141], v[162:165], v[122:125]
	v_mfma_f32_16x16x32_bf16 v[110:113], v[130:133], v[170:173], v[110:113]
	v_mfma_f32_16x16x32_bf16 v[106:109], v[138:141], v[170:173], v[106:109]
	v_mfma_f32_16x16x32_bf16 v[98:101], v[130:133], v[178:181], v[98:101]
	v_mfma_f32_16x16x32_bf16 v[90:93], v[138:141], v[178:181], v[90:93]
	v_mfma_f32_16x16x32_bf16 v[78:81], v[130:133], v[186:189], v[78:81]
	v_mfma_f32_16x16x32_bf16 v[74:77], v[138:141], v[186:189], v[74:77]
	v_mfma_f32_16x16x32_bf16 v[126:129], v[134:137], v[166:169], v[126:129]
	v_mfma_f32_16x16x32_bf16 v[122:125], v[142:145], v[166:169], v[122:125]
	v_mfma_f32_16x16x32_bf16 v[110:113], v[134:137], v[174:177], v[110:113]
	v_mfma_f32_16x16x32_bf16 v[106:109], v[142:145], v[174:177], v[106:109]
	v_mfma_f32_16x16x32_bf16 v[98:101], v[134:137], v[182:185], v[98:101]
	v_mfma_f32_16x16x32_bf16 v[90:93], v[142:145], v[182:185], v[90:93]
	v_mfma_f32_16x16x32_bf16 v[78:81], v[134:137], v[190:193], v[78:81]
	v_mfma_f32_16x16x32_bf16 v[74:77], v[142:145], v[190:193], v[74:77]
	v_mfma_f32_16x16x32_bf16 v[118:121], v[146:149], v[162:165], v[118:121]
	v_mfma_f32_16x16x32_bf16 v[114:117], v[154:157], v[162:165], v[114:117]
	v_mfma_f32_16x16x32_bf16 v[102:105], v[146:149], v[170:173], v[102:105]
	v_mfma_f32_16x16x32_bf16 v[94:97], v[154:157], v[170:173], v[94:97]
	v_mfma_f32_16x16x32_bf16 v[86:89], v[146:149], v[178:181], v[86:89]
	v_mfma_f32_16x16x32_bf16 v[82:85], v[154:157], v[178:181], v[82:85]
	v_mfma_f32_16x16x32_bf16 v[70:73], v[146:149], v[186:189], v[70:73]
	v_mfma_f32_16x16x32_bf16 v[66:69], v[154:157], v[186:189], v[66:69]
	v_mfma_f32_16x16x32_bf16 v[118:121], v[150:153], v[166:169], v[118:121]
	v_mfma_f32_16x16x32_bf16 v[114:117], v[158:161], v[166:169], v[114:117]
	v_mfma_f32_16x16x32_bf16 v[102:105], v[150:153], v[174:177], v[102:105]
	v_mfma_f32_16x16x32_bf16 v[94:97], v[158:161], v[174:177], v[94:97]
	v_mfma_f32_16x16x32_bf16 v[86:89], v[150:153], v[182:185], v[86:89]
	v_mfma_f32_16x16x32_bf16 v[82:85], v[158:161], v[182:185], v[82:85]
	v_mfma_f32_16x16x32_bf16 v[70:73], v[150:153], v[190:193], v[70:73]
	v_mfma_f32_16x16x32_bf16 v[66:69], v[158:161], v[190:193], v[66:69]
	s_setprio 0
	s_barrier
	s_add_u32 s22, s20, 0x8000
	s_addc_u32 s23, s21, 0
	s_add_i32 s36, s36, s31
	s_mov_b32 m0, s36
	ds_read_b128 v[162:165], v237 offset:49152
	ds_read_b128 v[166:169], v237 offset:50176
	ds_read_b128 v[170:173], v237 offset:51200
	ds_read_b128 v[174:177], v237 offset:52224
	ds_read_b128 v[178:181], v237 offset:53248
	ds_read_b128 v[182:185], v237 offset:54272
	ds_read_b128 v[186:189], v237 offset:55296
	ds_read_b128 v[190:193], v237 offset:56320
	global_load_lds_dwordx4 v210, s[22:23]
	s_add_i32 m0, s36, 0x2000
	s_add_u32 s20, s20, 0xc000
	s_addc_u32 s21, s21, 0
	global_load_lds_dwordx4 v214, s[22:23]
	s_add_i32 s22, s37, s31
	s_mov_b32 m0, s22
	v_lshl_add_u64 v[204:205], v[204:205], 0, s[88:89]
	global_load_lds_dwordx4 v210, s[20:21]
	s_add_i32 m0, s22, 0x2000
	s_nop 0
	global_load_lds_dwordx4 v214, s[20:21]
	s_mov_b32 m0, s58
	s_nop 0
	global_load_lds_dwordx4 v[204:205], off
	v_lshl_add_u64 v[204:205], v[206:207], 0, s[88:89]
	s_mov_b32 m0, s59
	s_nop 0
	global_load_lds_dwordx4 v[204:205], off
	s_waitcnt vmcnt(8)
	s_waitcnt lgkmcnt(0)
	s_barrier
	s_setprio 1
	s_waitcnt lgkmcnt(0)
	v_mfma_f32_16x16x32_bf16 v[62:65], v[130:133], v[162:165], v[62:65]
	v_mfma_f32_16x16x32_bf16 v[58:61], v[138:141], v[162:165], v[58:61]
	v_mfma_f32_16x16x32_bf16 v[46:49], v[130:133], v[170:173], v[46:49]
	v_mfma_f32_16x16x32_bf16 v[42:45], v[138:141], v[170:173], v[42:45]
	v_mfma_f32_16x16x32_bf16 v[34:37], v[130:133], v[178:181], v[34:37]
	v_mfma_f32_16x16x32_bf16 v[26:29], v[138:141], v[178:181], v[26:29]
	v_mfma_f32_16x16x32_bf16 v[14:17], v[130:133], v[186:189], v[14:17]
	v_mfma_f32_16x16x32_bf16 v[10:13], v[138:141], v[186:189], v[10:13]
	v_mfma_f32_16x16x32_bf16 v[62:65], v[134:137], v[166:169], v[62:65]
	v_mfma_f32_16x16x32_bf16 v[58:61], v[142:145], v[166:169], v[58:61]
	v_mfma_f32_16x16x32_bf16 v[46:49], v[134:137], v[174:177], v[46:49]
	v_mfma_f32_16x16x32_bf16 v[42:45], v[142:145], v[174:177], v[42:45]
	v_mfma_f32_16x16x32_bf16 v[34:37], v[134:137], v[182:185], v[34:37]
	v_mfma_f32_16x16x32_bf16 v[26:29], v[142:145], v[182:185], v[26:29]
	v_mfma_f32_16x16x32_bf16 v[14:17], v[134:137], v[190:193], v[14:17]
	v_mfma_f32_16x16x32_bf16 v[10:13], v[142:145], v[190:193], v[10:13]
	v_mfma_f32_16x16x32_bf16 v[54:57], v[146:149], v[162:165], v[54:57]
	v_mfma_f32_16x16x32_bf16 v[50:53], v[154:157], v[162:165], v[50:53]
	v_mfma_f32_16x16x32_bf16 v[38:41], v[146:149], v[170:173], v[38:41]
	v_mfma_f32_16x16x32_bf16 v[30:33], v[154:157], v[170:173], v[30:33]
	v_mfma_f32_16x16x32_bf16 v[22:25], v[146:149], v[178:181], v[22:25]
	v_mfma_f32_16x16x32_bf16 v[18:21], v[154:157], v[178:181], v[18:21]
	v_mfma_f32_16x16x32_bf16 v[6:9], v[146:149], v[186:189], v[6:9]
	v_mfma_f32_16x16x32_bf16 v[2:5], v[154:157], v[186:189], v[2:5]
	v_mfma_f32_16x16x32_bf16 v[54:57], v[150:153], v[166:169], v[54:57]
	v_mfma_f32_16x16x32_bf16 v[50:53], v[158:161], v[166:169], v[50:53]
	v_mfma_f32_16x16x32_bf16 v[38:41], v[150:153], v[174:177], v[38:41]
	v_mfma_f32_16x16x32_bf16 v[30:33], v[158:161], v[174:177], v[30:33]
	v_mfma_f32_16x16x32_bf16 v[22:25], v[150:153], v[182:185], v[22:25]
	v_mfma_f32_16x16x32_bf16 v[18:21], v[158:161], v[182:185], v[18:21]
	v_mfma_f32_16x16x32_bf16 v[6:9], v[150:153], v[190:193], v[6:9]
	v_mfma_f32_16x16x32_bf16 v[2:5], v[158:161], v[190:193], v[2:5]
	s_setprio 0
	s_barrier
	s_add_i32 s65, s65, 2
	s_add_u32 s63, s63, 0x10000
	s_addc_u32 s64, s64, 0
	s_add_u32 s18, s18, 0x100
	s_addc_u32 s19, s19, 0
	s_cmp_gt_u32 s65, 13
	s_cbranch_scc0 .LBB0_887
	s_and_b64 vcc, exec, s[6:7]
	s_cbranch_vccz .LBB0_890
	s_barrier

; #define PG8_STAGE(bufoff, gbase, voff) do { _Pragma("unroll") for (int _i = 0; _i < 2; ++_i) \
;         __builtin_amdgcn_global_load_lds((const unsigned*)((const char*)(gbase) + (voff)[_i]), (LAS unsigned*)(lds + (bufoff) + ldsw + _i * 8192), 16, 0, 0); } while (0)
; #define PG8_LDA(dst, b, h) do { _Pragma("unroll") for (int m = 0; m < 4; ++m) _Pragma("unroll") for (int k = 0; k < 2; ++k) dst[m][k] = *(const LAS bf16x8*)(lds + PG8_SA(b, h) + aoff + m * 2048 + k * 1024); } while (0)
; #define PG8_LDB(dst, b, h) do { _Pragma("unroll") for (int n = 0; n < 2; ++n) _Pragma("unroll") for (int k = 0; k < 2; ++k) dst[n][k] = *(const LAS bf16x8*)(lds + PG8_SB(b, h) + boff + n * 2048 + k * 1024); } while (0)
; #define PG8_MMA(ai, bj, At, Bt) do { __builtin_amdgcn_s_setprio(1); _Pragma("unroll") for (int m = 0; m < 4; ++m) _Pragma("unroll") for (int n = 0; n < 2; ++n) _Pragma("unroll") for (int k = 0; k < 2; ++k) \
;         acc[ai][bj][m][n] = __builtin_amdgcn_mfma_f32_16x16x32_bf16(Bt[n][k], At[m][k], acc[ai][bj][m][n], 0, 0, 0); __builtin_amdgcn_s_setprio(0); } while (0)
; #define PG8_WAIT_V(n) asm volatile("s_waitcnt vmcnt(" #n ")" ::: "memory")
; #define PG8_WAIT_L(n) asm volatile("s_waitcnt lgkmcnt(" #n ")" ::: "memory")
; #define PG8_BAR __builtin_amdgcn_s_barrier()
; #define PG8_SCHED __builtin_amdgcn_sched_barrier(0)
; template <class Epi, class Sched>
; __device__ __forceinline__ void gemm_phase(const int tid, LAS unsigned char* lds, const Gemm g, const Sched& S, const Epi& E) {
;     ...
;         for (int t = 0; t < nt; t += 2) {
;             const bool last = (t == nt - 2);
;             const char* a1 = cA + (size_t)(t + 1) * kstepA;
;             const char* a2 = last ? nA : cA + (size_t)(t + 2) * kstepA; const char* b2 = last ? nB : cB + (size_t)(t + 2) * kstepB;
;             const char* a3 = a2 + kstepA; const char* b3 = b2 + kstepB;
;             PG8_LDB(B0, 0, 0); PG8_LDB(B1, 0, 1); PG8_SCHED; PG8_LDA(At, 0, 0); PG8_STAGE(PG8_SA(1, 1), a1 + hstepA, voffA);
;             PG8_WAIT_V(8); PG8_WAIT_L(0); PG8_BAR; PG8_MMA(0, 0, At, B0); PG8_MMA(0, 1, At, B1); PG8_BAR; PG8_SCHED;
;             PG8_LDA(At, 0, 1); PG8_STAGE(PG8_SB(0, 0), b2, voffB); PG8_STAGE(PG8_SB(0, 1), b2 + hstepB, voffB); PG8_STAGE(PG8_SA(0, 0), a2, voffA);
;             PG8_WAIT_V(8); PG8_WAIT_L(0); PG8_BAR; PG8_MMA(1, 0, At, B0); PG8_MMA(1, 1, At, B1); PG8_BAR; PG8_SCHED;
.LBB0_962:
	s_add_u32 s18, s16, 0x4000
	s_addc_u32 s19, s17, 0
	s_cmp_eq_u32 s62, 28
	s_cselect_b32 s22, s58, s18
	s_cselect_b32 s23, s9, s19
	s_cselect_b32 s20, s59, s60
	s_cselect_b32 s21, s7, s61
	s_add_u32 s18, s22, 0x8000
	s_addc_u32 s19, s23, 0
	s_add_i32 s36, 16, 0x10000
	s_add_i32 s37, 16, 0x14000
	v_add_u32_e32 v148, s36, v157
	v_add_u32_e32 v168, s37, v157
	ds_read_b128 v[130:133], v148
	ds_read_b128 v[134:137], v148 offset:1024
	ds_read_b128 v[138:141], v148 offset:2048
	ds_read_b128 v[148:151], v148 offset:3072
	ds_read_b128 v[152:155], v168
	ds_read_b128 v[160:163], v168 offset:1024
	ds_read_b128 v[164:167], v168 offset:2048
	ds_read_b128 v[168:171], v168 offset:3072
	s_add_i32 m0, s34, 0xc000
	ds_read_b128 v[172:175], v159
	ds_read_b128 v[176:179], v159 offset:1024
	ds_read_b128 v[180:183], v159 offset:2048
	ds_read_b128 v[184:187], v159 offset:3072
	ds_read_b128 v[188:191], v159 offset:4096
	ds_read_b128 v[204:207], v159 offset:5120
	ds_read_b128 v[208:211], v159 offset:6144
	ds_read_b128 v[212:215], v159 offset:7168
	global_load_lds_dwordx4 v146, s[16:17]
	s_add_i32 m0, s34, 0xe000
	s_nop 0
	global_load_lds_dwordx4 v144, s[16:17]
	s_waitcnt vmcnt(8)
	s_waitcnt lgkmcnt(0)
	s_barrier
	s_setprio 1
	s_waitcnt lgkmcnt(0)
	v_mfma_f32_16x16x32_bf16 v[126:129], v[130:133], v[172:175], v[126:129]
	v_mfma_f32_16x16x32_bf16 v[122:125], v[138:141], v[172:175], v[122:125]
	v_mfma_f32_16x16x32_bf16 v[118:121], v[130:133], v[180:183], v[118:121]
	v_mfma_f32_16x16x32_bf16 v[106:109], v[138:141], v[180:183], v[106:109]
	v_mfma_f32_16x16x32_bf16 v[102:105], v[130:133], v[188:191], v[102:105]
	v_mfma_f32_16x16x32_bf16 v[90:93], v[138:141], v[188:191], v[90:93]
	v_mfma_f32_16x16x32_bf16 v[86:89], v[130:133], v[208:211], v[86:89]
	v_mfma_f32_16x16x32_bf16 v[74:77], v[138:141], v[208:211], v[74:77]
	v_mfma_f32_16x16x32_bf16 v[126:129], v[134:137], v[176:179], v[126:129]
	v_mfma_f32_16x16x32_bf16 v[122:125], v[148:151], v[176:179], v[122:125]
	v_mfma_f32_16x16x32_bf16 v[118:121], v[134:137], v[184:187], v[118:121]
	v_mfma_f32_16x16x32_bf16 v[106:109], v[148:151], v[184:187], v[106:109]
	v_mfma_f32_16x16x32_bf16 v[102:105], v[134:137], v[204:207], v[102:105]
	v_mfma_f32_16x16x32_bf16 v[90:93], v[148:151], v[204:207], v[90:93]
	v_mfma_f32_16x16x32_bf16 v[86:89], v[134:137], v[212:215], v[86:89]
	v_mfma_f32_16x16x32_bf16 v[74:77], v[148:151], v[212:215], v[74:77]
	v_mfma_f32_16x16x32_bf16 v[114:117], v[152:155], v[172:175], v[114:117]
	v_mfma_f32_16x16x32_bf16 v[110:113], v[164:167], v[172:175], v[110:113]
	v_mfma_f32_16x16x32_bf16 v[98:101], v[152:155], v[180:183], v[98:101]
	v_mfma_f32_16x16x32_bf16 v[94:97], v[164:167], v[180:183], v[94:97]
	v_mfma_f32_16x16x32_bf16 v[82:85], v[152:155], v[188:191], v[82:85]
	v_mfma_f32_16x16x32_bf16 v[78:81], v[164:167], v[188:191], v[78:81]
	v_mfma_f32_16x16x32_bf16 v[70:73], v[152:155], v[208:211], v[70:73]
	v_mfma_f32_16x16x32_bf16 v[66:69], v[164:167], v[208:211], v[66:69]
	v_mfma_f32_16x16x32_bf16 v[114:117], v[160:163], v[176:179], v[114:117]
	v_mfma_f32_16x16x32_bf16 v[110:113], v[168:171], v[176:179], v[110:113]
	v_mfma_f32_16x16x32_bf16 v[98:101], v[160:163], v[184:187], v[98:101]
	v_mfma_f32_16x16x32_bf16 v[94:97], v[168:171], v[184:187], v[94:97]
	v_mfma_f32_16x16x32_bf16 v[82:85], v[160:163], v[204:207], v[82:85]
	v_mfma_f32_16x16x32_bf16 v[78:81], v[168:171], v[204:207], v[78:81]
	v_mfma_f32_16x16x32_bf16 v[70:73], v[160:163], v[212:215], v[70:73]
	v_mfma_f32_16x16x32_bf16 v[66:69], v[168:171], v[212:215], v[66:69]
	s_setprio 0
	s_barrier
	s_add_i32 s36, s36, s31
	s_mov_b32 m0, s36
	ds_read_b128 v[172:175], v159 offset:16384
	ds_read_b128 v[176:179], v159 offset:17408
	ds_read_b128 v[180:183], v159 offset:18432
	ds_read_b128 v[184:187], v159 offset:19456
	ds_read_b128 v[188:191], v159 offset:20480
	ds_read_b128 v[204:207], v159 offset:21504
	ds_read_b128 v[208:211], v159 offset:22528
	ds_read_b128 v[212:215], v159 offset:23552
	global_load_lds_dwordx4 v0, s[20:21]
	s_add_i32 m0, s36, 0x2000
	s_add_u32 s64, s20, 0x4000
	s_addc_u32 s65, s21, 0
	s_add_i32 s36, s37, s31
	global_load_lds_dwordx4 v142, s[20:21]
	s_mov_b32 m0, s36
	s_nop 0
	global_load_lds_dwordx4 v0, s[64:65]
	s_add_i32 m0, s36, 0x2000
	s_nop 0
	global_load_lds_dwordx4 v142, s[64:65]
	s_mov_b32 m0, s34
	s_nop 0
	global_load_lds_dwordx4 v0, s[22:23]
	s_mov_b32 m0, s35
	s_nop 0
	global_load_lds_dwordx4 v142, s[22:23]
	s_waitcnt vmcnt(8)
	s_waitcnt lgkmcnt(0)
	s_barrier
	s_setprio 1
	s_waitcnt lgkmcnt(0)
	v_mfma_f32_16x16x32_bf16 v[62:65], v[130:133], v[172:175], v[62:65]
	v_mfma_f32_16x16x32_bf16 v[58:61], v[138:141], v[172:175], v[58:61]
	v_mfma_f32_16x16x32_bf16 v[54:57], v[130:133], v[180:183], v[54:57]
	v_mfma_f32_16x16x32_bf16 v[42:45], v[138:141], v[180:183], v[42:45]
	v_mfma_f32_16x16x32_bf16 v[38:41], v[130:133], v[188:191], v[38:41]
	v_mfma_f32_16x16x32_bf16 v[26:29], v[138:141], v[188:191], v[26:29]
	v_mfma_f32_16x16x32_bf16 v[22:25], v[130:133], v[208:211], v[22:25]
	v_mfma_f32_16x16x32_bf16 v[10:13], v[138:141], v[208:211], v[10:13]
	v_mfma_f32_16x16x32_bf16 v[62:65], v[134:137], v[176:179], v[62:65]
	v_mfma_f32_16x16x32_bf16 v[58:61], v[148:151], v[176:179], v[58:61]
	v_mfma_f32_16x16x32_bf16 v[54:57], v[134:137], v[184:187], v[54:57]
	v_mfma_f32_16x16x32_bf16 v[42:45], v[148:151], v[184:187], v[42:45]
	v_mfma_f32_16x16x32_bf16 v[38:41], v[134:137], v[204:207], v[38:41]
	v_mfma_f32_16x16x32_bf16 v[26:29], v[148:151], v[204:207], v[26:29]
	v_mfma_f32_16x16x32_bf16 v[22:25], v[134:137], v[212:215], v[22:25]
	v_mfma_f32_16x16x32_bf16 v[10:13], v[148:151], v[212:215], v[10:13]
	v_mfma_f32_16x16x32_bf16 v[50:53], v[152:155], v[172:175], v[50:53]
	v_mfma_f32_16x16x32_bf16 v[46:49], v[164:167], v[172:175], v[46:49]
	v_mfma_f32_16x16x32_bf16 v[34:37], v[152:155], v[180:183], v[34:37]
	v_mfma_f32_16x16x32_bf16 v[30:33], v[164:167], v[180:183], v[30:33]
	v_mfma_f32_16x16x32_bf16 v[18:21], v[152:155], v[188:191], v[18:21]
	v_mfma_f32_16x16x32_bf16 v[14:17], v[164:167], v[188:191], v[14:17]
	v_mfma_f32_16x16x32_bf16 v[6:9], v[152:155], v[208:211], v[6:9]
	v_mfma_f32_16x16x32_bf16 v[2:5], v[164:167], v[208:211], v[2:5]
	v_mfma_f32_16x16x32_bf16 v[50:53], v[160:163], v[176:179], v[50:53]
	v_mfma_f32_16x16x32_bf16 v[46:49], v[168:171], v[176:179], v[46:49]
	v_mfma_f32_16x16x32_bf16 v[34:37], v[160:163], v[184:187], v[34:37]
	v_mfma_f32_16x16x32_bf16 v[30:33], v[168:171], v[184:187], v[30:33]
	v_mfma_f32_16x16x32_bf16 v[18:21], v[160:163], v[204:207], v[18:21]
	v_mfma_f32_16x16x32_bf16 v[14:17], v[168:171], v[204:207], v[14:17]
	v_mfma_f32_16x16x32_bf16 v[6:9], v[160:163], v[212:215], v[6:9]
	v_mfma_f32_16x16x32_bf16 v[2:5], v[168:171], v[212:215], v[2:5]
	s_setprio 0
	s_barrier
; #define PG8_STAGE(bufoff, gbase, voff) do { _Pragma("unroll") for (int _i = 0; _i < 2; ++_i) \
;         __builtin_amdgcn_global_load_lds((const unsigned*)((const char*)(gbase) + (voff)[_i]), (LAS unsigned*)(lds + (bufoff) + ldsw + _i * 8192), 16, 0, 0); } while (0)
; #define PG8_LDA(dst, b, h) do { _Pragma("unroll") for (int m = 0; m < 4; ++m) _Pragma("unroll") for (int k = 0; k < 2; ++k) dst[m][k] = *(const LAS bf16x8*)(lds + PG8_SA(b, h) + aoff + m * 2048 + k * 1024); } while (0)
; #define PG8_LDB(dst, b, h) do { _Pragma("unroll") for (int n = 0; n < 2; ++n) _Pragma("unroll") for (int k = 0; k < 2; ++k) dst[n][k] = *(const LAS bf16x8*)(lds + PG8_SB(b, h) + boff + n * 2048 + k * 1024); } while (0)
; #define PG8_MMA(ai, bj, At, Bt) do { __builtin_amdgcn_s_setprio(1); _Pragma("unroll") for (int m = 0; m < 4; ++m) _Pragma("unroll") for (int n = 0; n < 2; ++n) _Pragma("unroll") for (int k = 0; k < 2; ++k) \
;         acc[ai][bj][m][n] = __builtin_amdgcn_mfma_f32_16x16x32_bf16(Bt[n][k], At[m][k], acc[ai][bj][m][n], 0, 0, 0); __builtin_amdgcn_s_setprio(0); } while (0)
; #define PG8_WAIT_V(n) asm volatile("s_waitcnt vmcnt(" #n ")" ::: "memory")
; #define PG8_WAIT_L(n) asm volatile("s_waitcnt lgkmcnt(" #n ")" ::: "memory")
; #define PG8_BAR __builtin_amdgcn_s_barrier()
; #define PG8_SCHED __builtin_amdgcn_sched_barrier(0)
; template <class Epi, class Sched>
; __device__ __forceinline__ void gemm_phase(const int tid, LAS unsigned char* lds, const Gemm g, const Sched& S, const Epi& E) {
;     ...
;             PG8_LDB(B0, 1, 0); PG8_LDB(B1, 1, 1); PG8_SCHED; PG8_LDA(At, 1, 0); PG8_STAGE(PG8_SA(0, 1), a2 + hstepA, voffA);
;             PG8_WAIT_V(8); PG8_WAIT_L(0); PG8_BAR; PG8_MMA(0, 0, At, B0); PG8_MMA(0, 1, At, B1); PG8_BAR; PG8_SCHED;
;             PG8_LDA(At, 1, 1); PG8_STAGE(PG8_SB(1, 0), b3, voffB); PG8_STAGE(PG8_SB(1, 1), b3 + hstepB, voffB); PG8_STAGE(PG8_SA(1, 0), a3, voffA);
;             PG8_WAIT_V(8); PG8_WAIT_L(0); PG8_BAR; PG8_MMA(1, 0, At, B0); PG8_MMA(1, 1, At, B1); PG8_BAR; PG8_SCHED;
;         }
;         if (wr == 0) PG8_BAR;
	s_add_i32 s36, 16, 0x18000
	s_add_i32 s37, 16, 0x1c000
	v_add_u32_e32 v148, s36, v157
	v_add_u32_e32 v168, s37, v157
	ds_read_b128 v[130:133], v148
	ds_read_b128 v[134:137], v148 offset:1024
	ds_read_b128 v[138:141], v148 offset:2048
	ds_read_b128 v[148:151], v148 offset:3072
	ds_read_b128 v[152:155], v168
	ds_read_b128 v[160:163], v168 offset:1024
	ds_read_b128 v[164:167], v168 offset:2048
	ds_read_b128 v[168:171], v168 offset:3072
	s_add_u32 s22, s22, 0x4000
	s_addc_u32 s23, s23, 0
	s_mov_b32 m0, s52
	ds_read_b128 v[172:175], v159 offset:32768
	ds_read_b128 v[176:179], v159 offset:33792
	ds_read_b128 v[180:183], v159 offset:34816
	ds_read_b128 v[184:187], v159 offset:35840
	ds_read_b128 v[188:191], v159 offset:36864
	ds_read_b128 v[204:207], v159 offset:37888
	ds_read_b128 v[208:211], v159 offset:38912
	ds_read_b128 v[212:215], v159 offset:39936
	global_load_lds_dwordx4 v0, s[22:23]
	s_mov_b32 m0, s53
	s_nop 0
	global_load_lds_dwordx4 v142, s[22:23]
	s_waitcnt vmcnt(8)
	s_waitcnt lgkmcnt(0)
	s_barrier
	s_setprio 1
	s_waitcnt lgkmcnt(0)
	v_mfma_f32_16x16x32_bf16 v[126:129], v[130:133], v[172:175], v[126:129]
	v_mfma_f32_16x16x32_bf16 v[122:125], v[138:141], v[172:175], v[122:125]
	v_mfma_f32_16x16x32_bf16 v[118:121], v[130:133], v[180:183], v[118:121]
	v_mfma_f32_16x16x32_bf16 v[106:109], v[138:141], v[180:183], v[106:109]
	v_mfma_f32_16x16x32_bf16 v[102:105], v[130:133], v[188:191], v[102:105]
	v_mfma_f32_16x16x32_bf16 v[90:93], v[138:141], v[188:191], v[90:93]
	v_mfma_f32_16x16x32_bf16 v[86:89], v[130:133], v[208:211], v[86:89]
	v_mfma_f32_16x16x32_bf16 v[74:77], v[138:141], v[208:211], v[74:77]
	v_mfma_f32_16x16x32_bf16 v[126:129], v[134:137], v[176:179], v[126:129]
	v_mfma_f32_16x16x32_bf16 v[122:125], v[148:151], v[176:179], v[122:125]
	v_mfma_f32_16x16x32_bf16 v[118:121], v[134:137], v[184:187], v[118:121]
	v_mfma_f32_16x16x32_bf16 v[106:109], v[148:151], v[184:187], v[106:109]
	v_mfma_f32_16x16x32_bf16 v[102:105], v[134:137], v[204:207], v[102:105]
	v_mfma_f32_16x16x32_bf16 v[90:93], v[148:151], v[204:207], v[90:93]
	v_mfma_f32_16x16x32_bf16 v[86:89], v[134:137], v[212:215], v[86:89]
	v_mfma_f32_16x16x32_bf16 v[74:77], v[148:151], v[212:215], v[74:77]
	v_mfma_f32_16x16x32_bf16 v[114:117], v[152:155], v[172:175], v[114:117]
	v_mfma_f32_16x16x32_bf16 v[110:113], v[164:167], v[172:175], v[110:113]
	v_mfma_f32_16x16x32_bf16 v[98:101], v[152:155], v[180:183], v[98:101]
	v_mfma_f32_16x16x32_bf16 v[94:97], v[164:167], v[180:183], v[94:97]
	v_mfma_f32_16x16x32_bf16 v[82:85], v[152:155], v[188:191], v[82:85]
	v_mfma_f32_16x16x32_bf16 v[78:81], v[164:167], v[188:191], v[78:81]
	v_mfma_f32_16x16x32_bf16 v[70:73], v[152:155], v[208:211], v[70:73]
	v_mfma_f32_16x16x32_bf16 v[66:69], v[164:167], v[208:211], v[66:69]
	v_mfma_f32_16x16x32_bf16 v[114:117], v[160:163], v[176:179], v[114:117]
	v_mfma_f32_16x16x32_bf16 v[110:113], v[168:171], v[176:179], v[110:113]
	v_mfma_f32_16x16x32_bf16 v[98:101], v[160:163], v[184:187], v[98:101]
	v_mfma_f32_16x16x32_bf16 v[94:97], v[168:171], v[184:187], v[94:97]
	v_mfma_f32_16x16x32_bf16 v[82:85], v[160:163], v[204:207], v[82:85]
	v_mfma_f32_16x16x32_bf16 v[78:81], v[168:171], v[204:207], v[78:81]
	v_mfma_f32_16x16x32_bf16 v[70:73], v[160:163], v[212:215], v[70:73]
	v_mfma_f32_16x16x32_bf16 v[66:69], v[168:171], v[212:215], v[66:69]
	s_setprio 0
	s_barrier
	s_add_u32 s22, s20, 0x8000
	s_addc_u32 s23, s21, 0
	s_add_i32 s36, s36, s31
	s_mov_b32 m0, s36
	ds_read_b128 v[172:175], v159 offset:49152
	ds_read_b128 v[176:179], v159 offset:50176
	ds_read_b128 v[180:183], v159 offset:51200
	ds_read_b128 v[184:187], v159 offset:52224
	ds_read_b128 v[188:191], v159 offset:53248
	ds_read_b128 v[204:207], v159 offset:54272
	ds_read_b128 v[208:211], v159 offset:55296
	ds_read_b128 v[212:215], v159 offset:56320
	global_load_lds_dwordx4 v0, s[22:23]
	s_add_i32 m0, s36, 0x2000
	s_add_u32 s20, s20, 0xc000
	s_addc_u32 s21, s21, 0
	global_load_lds_dwordx4 v142, s[22:23]
	s_add_i32 s22, s37, s31
	s_mov_b32 m0, s22
	s_nop 0
	global_load_lds_dwordx4 v0, s[20:21]
	s_add_i32 m0, s22, 0x2000
	s_nop 0
	global_load_lds_dwordx4 v142, s[20:21]
	s_mov_b32 m0, s54
	s_nop 0
	global_load_lds_dwordx4 v0, s[18:19]
	s_mov_b32 m0, s55
	s_nop 0
	global_load_lds_dwordx4 v142, s[18:19]
	s_waitcnt vmcnt(8)
	s_waitcnt lgkmcnt(0)
	s_barrier
	s_setprio 1
	s_waitcnt lgkmcnt(0)
	v_mfma_f32_16x16x32_bf16 v[62:65], v[130:133], v[172:175], v[62:65]
	v_mfma_f32_16x16x32_bf16 v[58:61], v[138:141], v[172:175], v[58:61]
	v_mfma_f32_16x16x32_bf16 v[54:57], v[130:133], v[180:183], v[54:57]
	v_mfma_f32_16x16x32_bf16 v[42:45], v[138:141], v[180:183], v[42:45]
	v_mfma_f32_16x16x32_bf16 v[38:41], v[130:133], v[188:191], v[38:41]
	v_mfma_f32_16x16x32_bf16 v[26:29], v[138:141], v[188:191], v[26:29]
	v_mfma_f32_16x16x32_bf16 v[22:25], v[130:133], v[208:211], v[22:25]
	v_mfma_f32_16x16x32_bf16 v[10:13], v[138:141], v[208:211], v[10:13]
	v_mfma_f32_16x16x32_bf16 v[62:65], v[134:137], v[176:179], v[62:65]
	v_mfma_f32_16x16x32_bf16 v[58:61], v[148:151], v[176:179], v[58:61]
	v_mfma_f32_16x16x32_bf16 v[54:57], v[134:137], v[184:187], v[54:57]
	v_mfma_f32_16x16x32_bf16 v[42:45], v[148:151], v[184:187], v[42:45]
	v_mfma_f32_16x16x32_bf16 v[38:41], v[134:137], v[204:207], v[38:41]
	v_mfma_f32_16x16x32_bf16 v[26:29], v[148:151], v[204:207], v[26:29]
	v_mfma_f32_16x16x32_bf16 v[22:25], v[134:137], v[212:215], v[22:25]
	v_mfma_f32_16x16x32_bf16 v[10:13], v[148:151], v[212:215], v[10:13]
	v_mfma_f32_16x16x32_bf16 v[50:53], v[152:155], v[172:175], v[50:53]
	v_mfma_f32_16x16x32_bf16 v[46:49], v[164:167], v[172:175], v[46:49]
	v_mfma_f32_16x16x32_bf16 v[34:37], v[152:155], v[180:183], v[34:37]
	v_mfma_f32_16x16x32_bf16 v[30:33], v[164:167], v[180:183], v[30:33]
	v_mfma_f32_16x16x32_bf16 v[18:21], v[152:155], v[188:191], v[18:21]
	v_mfma_f32_16x16x32_bf16 v[14:17], v[164:167], v[188:191], v[14:17]
	v_mfma_f32_16x16x32_bf16 v[6:9], v[152:155], v[208:211], v[6:9]
	v_mfma_f32_16x16x32_bf16 v[2:5], v[164:167], v[208:211], v[2:5]
	v_mfma_f32_16x16x32_bf16 v[50:53], v[160:163], v[176:179], v[50:53]
	v_mfma_f32_16x16x32_bf16 v[46:49], v[168:171], v[176:179], v[46:49]
	v_mfma_f32_16x16x32_bf16 v[34:37], v[160:163], v[184:187], v[34:37]
	v_mfma_f32_16x16x32_bf16 v[30:33], v[168:171], v[184:187], v[30:33]
	v_mfma_f32_16x16x32_bf16 v[18:21], v[160:163], v[204:207], v[18:21]
	v_mfma_f32_16x16x32_bf16 v[14:17], v[168:171], v[204:207], v[14:17]
	v_mfma_f32_16x16x32_bf16 v[6:9], v[160:163], v[212:215], v[6:9]
	v_mfma_f32_16x16x32_bf16 v[2:5], v[168:171], v[212:215], v[2:5]
	s_setprio 0
	s_barrier
	s_add_i32 s62, s62, 2
	s_add_u32 s60, s60, 0x10000
	s_addc_u32 s61, s61, 0
	s_add_u32 s16, s16, 0x10000
	s_addc_u32 s17, s17, 0
	s_cmp_gt_u32 s62, 29
	s_cbranch_scc0 .LBB0_962
	s_and_b64 vcc, exec, s[2:3]
	s_cbranch_vccz .LBB0_965
	s_barrier

; #define PG8_STAGE(bufoff, gbase, voff) do { _Pragma("unroll") for (int _i = 0; _i < 2; ++_i) \
;         __builtin_amdgcn_global_load_lds((const unsigned*)((const char*)(gbase) + (voff)[_i]), (LAS unsigned*)(lds + (bufoff) + ldsw + _i * 8192), 16, 0, 0); } while (0)
; #define PG8_LDA(dst, b, h) do { _Pragma("unroll") for (int m = 0; m < 4; ++m) _Pragma("unroll") for (int k = 0; k < 2; ++k) dst[m][k] = *(const LAS bf16x8*)(lds + PG8_SA(b, h) + aoff + m * 2048 + k * 1024); } while (0)
; #define PG8_LDB(dst, b, h) do { _Pragma("unroll") for (int n = 0; n < 2; ++n) _Pragma("unroll") for (int k = 0; k < 2; ++k) dst[n][k] = *(const LAS bf16x8*)(lds + PG8_SB(b, h) + boff + n * 2048 + k * 1024); } while (0)
; #define PG8_MMA(ai, bj, At, Bt) do { __builtin_amdgcn_s_setprio(1); _Pragma("unroll") for (int m = 0; m < 4; ++m) _Pragma("unroll") for (int n = 0; n < 2; ++n) _Pragma("unroll") for (int k = 0; k < 2; ++k) \
;         acc[ai][bj][m][n] = __builtin_amdgcn_mfma_f32_16x16x32_bf16(Bt[n][k], At[m][k], acc[ai][bj][m][n], 0, 0, 0); __builtin_amdgcn_s_setprio(0); } while (0)
; #define PG8_WAIT_V(n) asm volatile("s_waitcnt vmcnt(" #n ")" ::: "memory")
; #define PG8_WAIT_L(n) asm volatile("s_waitcnt lgkmcnt(" #n ")" ::: "memory")
; #define PG8_BAR __builtin_amdgcn_s_barrier()
; #define PG8_SCHED __builtin_amdgcn_sched_barrier(0)
; template <class Epi, class Sched>
; __device__ __forceinline__ void gemm_phase(const int tid, LAS unsigned char* lds, const Gemm g, const Sched& S, const Epi& E) {
;     ...
;         for (int t = 0; t < nt; t += 2) {
;             const bool last = (t == nt - 2);
;             const char* a1 = cA + (size_t)(t + 1) * kstepA;
;             const char* a2 = last ? nA : cA + (size_t)(t + 2) * kstepA; const char* b2 = last ? nB : cB + (size_t)(t + 2) * kstepB;
;             const char* a3 = a2 + kstepA; const char* b3 = b2 + kstepB;
;             PG8_LDB(B0, 0, 0); PG8_LDB(B1, 0, 1); PG8_SCHED; PG8_LDA(At, 0, 0); PG8_STAGE(PG8_SA(1, 1), a1 + hstepA, voffA);
;             PG8_WAIT_V(8); PG8_WAIT_L(0); PG8_BAR; PG8_MMA(0, 0, At, B0); PG8_MMA(0, 1, At, B1); PG8_BAR; PG8_SCHED;
;             PG8_LDA(At, 0, 1); PG8_STAGE(PG8_SB(0, 0), b2, voffB); PG8_STAGE(PG8_SB(0, 1), b2 + hstepB, voffB); PG8_STAGE(PG8_SA(0, 0), a2, voffA);
;             PG8_WAIT_V(8); PG8_WAIT_L(0); PG8_BAR; PG8_MMA(1, 0, At, B0); PG8_MMA(1, 1, At, B1); PG8_BAR; PG8_SCHED;
.LBB0_1100:
	s_add_u32 s22, s20, 0x4000
	s_addc_u32 s23, s21, 0
	s_cmp_eq_u32 s76, 28
	s_cselect_b32 s26, s64, s22
	s_cselect_b32 s27, s13, s23
	s_cselect_b32 s24, s65, s66
	s_cselect_b32 s25, s11, s67
	s_add_u32 s22, s26, 0x8000
	s_addc_u32 s23, s27, 0
	s_add_i32 s36, 16, 0x10000
	v_add_u32_e32 v0, s36, v145
	s_add_i32 s37, 16, 0x14000
	ds_read_b128 v[148:151], v0
	ds_read_b128 v[152:155], v0 offset:1024
	ds_read_b128 v[156:159], v0 offset:2048
	ds_read_b128 v[160:163], v0 offset:3072
	v_add_u32_e32 v0, s37, v145
	ds_read_b128 v[164:167], v0
	ds_read_b128 v[168:171], v0 offset:1024
	ds_read_b128 v[172:175], v0 offset:2048
	ds_read_b128 v[176:179], v0 offset:3072
	s_add_i32 m0, s19, 0xc000
	ds_read_b128 v[180:183], v146
	ds_read_b128 v[184:187], v146 offset:1024
	ds_read_b128 v[188:191], v146 offset:2048
	ds_read_b128 v[204:207], v146 offset:3072
	ds_read_b128 v[208:211], v146 offset:4096
	ds_read_b128 v[212:215], v146 offset:5120
	ds_read_b128 v[216:219], v146 offset:6144
	ds_read_b128 v[220:223], v146 offset:7168
	global_load_lds_dwordx4 v140, s[20:21]
	s_add_i32 m0, s19, 0xe000
	s_nop 0
	global_load_lds_dwordx4 v138, s[20:21]
	s_waitcnt vmcnt(8)
	s_waitcnt lgkmcnt(0)
	s_barrier
	s_setprio 1
	s_waitcnt lgkmcnt(0)
	v_mfma_f32_16x16x32_bf16 v[126:129], v[148:151], v[180:183], v[126:129]
	v_mfma_f32_16x16x32_bf16 v[122:125], v[156:159], v[180:183], v[122:125]
	v_mfma_f32_16x16x32_bf16 v[110:113], v[148:151], v[188:191], v[110:113]
	v_mfma_f32_16x16x32_bf16 v[106:109], v[156:159], v[188:191], v[106:109]
	v_mfma_f32_16x16x32_bf16 v[94:97], v[148:151], v[208:211], v[94:97]
	v_mfma_f32_16x16x32_bf16 v[90:93], v[156:159], v[208:211], v[90:93]
	v_mfma_f32_16x16x32_bf16 v[78:81], v[148:151], v[216:219], v[78:81]
	v_mfma_f32_16x16x32_bf16 v[74:77], v[156:159], v[216:219], v[74:77]
	v_mfma_f32_16x16x32_bf16 v[126:129], v[152:155], v[184:187], v[126:129]
	v_mfma_f32_16x16x32_bf16 v[122:125], v[160:163], v[184:187], v[122:125]
	v_mfma_f32_16x16x32_bf16 v[110:113], v[152:155], v[204:207], v[110:113]
	v_mfma_f32_16x16x32_bf16 v[106:109], v[160:163], v[204:207], v[106:109]
	v_mfma_f32_16x16x32_bf16 v[94:97], v[152:155], v[212:215], v[94:97]
	v_mfma_f32_16x16x32_bf16 v[90:93], v[160:163], v[212:215], v[90:93]
	v_mfma_f32_16x16x32_bf16 v[78:81], v[152:155], v[220:223], v[78:81]
	v_mfma_f32_16x16x32_bf16 v[74:77], v[160:163], v[220:223], v[74:77]
	v_mfma_f32_16x16x32_bf16 v[118:121], v[164:167], v[180:183], v[118:121]
	v_mfma_f32_16x16x32_bf16 v[114:117], v[172:175], v[180:183], v[114:117]
	v_mfma_f32_16x16x32_bf16 v[102:105], v[164:167], v[188:191], v[102:105]
	v_mfma_f32_16x16x32_bf16 v[98:101], v[172:175], v[188:191], v[98:101]
	v_mfma_f32_16x16x32_bf16 v[86:89], v[164:167], v[208:211], v[86:89]
	v_mfma_f32_16x16x32_bf16 v[82:85], v[172:175], v[208:211], v[82:85]
	v_mfma_f32_16x16x32_bf16 v[70:73], v[164:167], v[216:219], v[70:73]
	v_mfma_f32_16x16x32_bf16 v[66:69], v[172:175], v[216:219], v[66:69]
	v_mfma_f32_16x16x32_bf16 v[118:121], v[168:171], v[184:187], v[118:121]
	v_mfma_f32_16x16x32_bf16 v[114:117], v[176:179], v[184:187], v[114:117]
	v_mfma_f32_16x16x32_bf16 v[102:105], v[168:171], v[204:207], v[102:105]
	v_mfma_f32_16x16x32_bf16 v[98:101], v[176:179], v[204:207], v[98:101]
	v_mfma_f32_16x16x32_bf16 v[86:89], v[168:171], v[212:215], v[86:89]
	v_mfma_f32_16x16x32_bf16 v[82:85], v[176:179], v[212:215], v[82:85]
	v_mfma_f32_16x16x32_bf16 v[70:73], v[168:171], v[220:223], v[70:73]
	v_mfma_f32_16x16x32_bf16 v[66:69], v[176:179], v[220:223], v[66:69]
	s_setprio 0
	s_barrier
	s_add_i32 s36, s36, s52
	s_mov_b32 m0, s36
	ds_read_b128 v[180:183], v146 offset:16384
	ds_read_b128 v[184:187], v146 offset:17408
	ds_read_b128 v[188:191], v146 offset:18432
	ds_read_b128 v[204:207], v146 offset:19456
	ds_read_b128 v[208:211], v146 offset:20480
	ds_read_b128 v[212:215], v146 offset:21504
	ds_read_b128 v[216:219], v146 offset:22528
	ds_read_b128 v[220:223], v146 offset:23552
	global_load_lds_dwordx4 v134, s[24:25]
	s_add_i32 m0, s36, 0x2000
	s_add_u32 s78, s24, 0x4000
	s_addc_u32 s79, s25, 0
	s_add_i32 s36, s37, s52
	global_load_lds_dwordx4 v130, s[24:25]
	s_mov_b32 m0, s36
	s_nop 0
	global_load_lds_dwordx4 v134, s[78:79]
	s_add_i32 m0, s36, 0x2000
	s_nop 0
	global_load_lds_dwordx4 v130, s[78:79]
	s_mov_b32 m0, s19
	s_nop 0
	global_load_lds_dwordx4 v136, s[26:27]
	s_mov_b32 m0, s54
	s_nop 0
	global_load_lds_dwordx4 v132, s[26:27]
	s_waitcnt vmcnt(8)
	s_waitcnt lgkmcnt(0)
	s_barrier
	s_setprio 1
	s_waitcnt lgkmcnt(0)
	v_mfma_f32_16x16x32_bf16 v[62:65], v[148:151], v[180:183], v[62:65]
	v_mfma_f32_16x16x32_bf16 v[58:61], v[156:159], v[180:183], v[58:61]
	v_mfma_f32_16x16x32_bf16 v[46:49], v[148:151], v[188:191], v[46:49]
	v_mfma_f32_16x16x32_bf16 v[42:45], v[156:159], v[188:191], v[42:45]
	v_mfma_f32_16x16x32_bf16 v[30:33], v[148:151], v[208:211], v[30:33]
	v_mfma_f32_16x16x32_bf16 v[26:29], v[156:159], v[208:211], v[26:29]
	v_mfma_f32_16x16x32_bf16 v[14:17], v[148:151], v[216:219], v[14:17]
	v_mfma_f32_16x16x32_bf16 v[10:13], v[156:159], v[216:219], v[10:13]
	v_mfma_f32_16x16x32_bf16 v[62:65], v[152:155], v[184:187], v[62:65]
	v_mfma_f32_16x16x32_bf16 v[58:61], v[160:163], v[184:187], v[58:61]
	v_mfma_f32_16x16x32_bf16 v[46:49], v[152:155], v[204:207], v[46:49]
	v_mfma_f32_16x16x32_bf16 v[42:45], v[160:163], v[204:207], v[42:45]
	v_mfma_f32_16x16x32_bf16 v[30:33], v[152:155], v[212:215], v[30:33]
	v_mfma_f32_16x16x32_bf16 v[26:29], v[160:163], v[212:215], v[26:29]
	v_mfma_f32_16x16x32_bf16 v[14:17], v[152:155], v[220:223], v[14:17]
	v_mfma_f32_16x16x32_bf16 v[10:13], v[160:163], v[220:223], v[10:13]
	v_mfma_f32_16x16x32_bf16 v[54:57], v[164:167], v[180:183], v[54:57]
	v_mfma_f32_16x16x32_bf16 v[50:53], v[172:175], v[180:183], v[50:53]
	v_mfma_f32_16x16x32_bf16 v[38:41], v[164:167], v[188:191], v[38:41]
	v_mfma_f32_16x16x32_bf16 v[34:37], v[172:175], v[188:191], v[34:37]
	v_mfma_f32_16x16x32_bf16 v[22:25], v[164:167], v[208:211], v[22:25]
	v_mfma_f32_16x16x32_bf16 v[18:21], v[172:175], v[208:211], v[18:21]
	v_mfma_f32_16x16x32_bf16 v[6:9], v[164:167], v[216:219], v[6:9]
	v_mfma_f32_16x16x32_bf16 v[2:5], v[172:175], v[216:219], v[2:5]
	v_mfma_f32_16x16x32_bf16 v[54:57], v[168:171], v[184:187], v[54:57]
	v_mfma_f32_16x16x32_bf16 v[50:53], v[176:179], v[184:187], v[50:53]
	v_mfma_f32_16x16x32_bf16 v[38:41], v[168:171], v[204:207], v[38:41]
	v_mfma_f32_16x16x32_bf16 v[34:37], v[176:179], v[204:207], v[34:37]
	v_mfma_f32_16x16x32_bf16 v[22:25], v[168:171], v[212:215], v[22:25]
	v_mfma_f32_16x16x32_bf16 v[18:21], v[176:179], v[212:215], v[18:21]
	v_mfma_f32_16x16x32_bf16 v[6:9], v[168:171], v[220:223], v[6:9]
	v_mfma_f32_16x16x32_bf16 v[2:5], v[176:179], v[220:223], v[2:5]
	s_setprio 0
	s_barrier
; #define PG8_STAGE(bufoff, gbase, voff) do { _Pragma("unroll") for (int _i = 0; _i < 2; ++_i) \
;         __builtin_amdgcn_global_load_lds((const unsigned*)((const char*)(gbase) + (voff)[_i]), (LAS unsigned*)(lds + (bufoff) + ldsw + _i * 8192), 16, 0, 0); } while (0)
; #define PG8_LDA(dst, b, h) do { _Pragma("unroll") for (int m = 0; m < 4; ++m) _Pragma("unroll") for (int k = 0; k < 2; ++k) dst[m][k] = *(const LAS bf16x8*)(lds + PG8_SA(b, h) + aoff + m * 2048 + k * 1024); } while (0)
; #define PG8_LDB(dst, b, h) do { _Pragma("unroll") for (int n = 0; n < 2; ++n) _Pragma("unroll") for (int k = 0; k < 2; ++k) dst[n][k] = *(const LAS bf16x8*)(lds + PG8_SB(b, h) + boff + n * 2048 + k * 1024); } while (0)
; #define PG8_MMA(ai, bj, At, Bt) do { __builtin_amdgcn_s_setprio(1); _Pragma("unroll") for (int m = 0; m < 4; ++m) _Pragma("unroll") for (int n = 0; n < 2; ++n) _Pragma("unroll") for (int k = 0; k < 2; ++k) \
;         acc[ai][bj][m][n] = __builtin_amdgcn_mfma_f32_16x16x32_bf16(Bt[n][k], At[m][k], acc[ai][bj][m][n], 0, 0, 0); __builtin_amdgcn_s_setprio(0); } while (0)
; #define PG8_WAIT_V(n) asm volatile("s_waitcnt vmcnt(" #n ")" ::: "memory")
; #define PG8_WAIT_L(n) asm volatile("s_waitcnt lgkmcnt(" #n ")" ::: "memory")
; #define PG8_BAR __builtin_amdgcn_s_barrier()
; #define PG8_SCHED __builtin_amdgcn_sched_barrier(0)
; template <class Epi, class Sched>
; __device__ __forceinline__ void gemm_phase(const int tid, LAS unsigned char* lds, const Gemm g, const Sched& S, const Epi& E) {
;     ...
;             PG8_LDB(B0, 1, 0); PG8_LDB(B1, 1, 1); PG8_SCHED; PG8_LDA(At, 1, 0); PG8_STAGE(PG8_SA(0, 1), a2 + hstepA, voffA);
;             PG8_WAIT_V(8); PG8_WAIT_L(0); PG8_BAR; PG8_MMA(0, 0, At, B0); PG8_MMA(0, 1, At, B1); PG8_BAR; PG8_SCHED;
;             PG8_LDA(At, 1, 1); PG8_STAGE(PG8_SB(1, 0), b3, voffB); PG8_STAGE(PG8_SB(1, 1), b3 + hstepB, voffB); PG8_STAGE(PG8_SA(1, 0), a3, voffA);
;             PG8_WAIT_V(8); PG8_WAIT_L(0); PG8_BAR; PG8_MMA(1, 0, At, B0); PG8_MMA(1, 1, At, B1); PG8_BAR; PG8_SCHED;
;         }
;         if (wr == 0) PG8_BAR;
	s_add_i32 s36, 16, 0x18000
	v_add_u32_e32 v0, s36, v145
	s_add_i32 s37, 16, 0x1c000
	ds_read_b128 v[148:151], v0
	ds_read_b128 v[152:155], v0 offset:1024
	ds_read_b128 v[156:159], v0 offset:2048
	ds_read_b128 v[160:163], v0 offset:3072
	v_add_u32_e32 v0, s37, v145
	ds_read_b128 v[164:167], v0
	ds_read_b128 v[168:171], v0 offset:1024
	ds_read_b128 v[172:175], v0 offset:2048
	ds_read_b128 v[176:179], v0 offset:3072
	s_add_u32 s26, s26, 0x4000
	s_addc_u32 s27, s27, 0
	s_mov_b32 m0, s55
	ds_read_b128 v[180:183], v146 offset:32768
	ds_read_b128 v[184:187], v146 offset:33792
	ds_read_b128 v[188:191], v146 offset:34816
	ds_read_b128 v[204:207], v146 offset:35840
	ds_read_b128 v[208:211], v146 offset:36864
	ds_read_b128 v[212:215], v146 offset:37888
	ds_read_b128 v[216:219], v146 offset:38912
	ds_read_b128 v[220:223], v146 offset:39936
	global_load_lds_dwordx4 v136, s[26:27]
	s_mov_b32 m0, s56
	s_nop 0
	global_load_lds_dwordx4 v132, s[26:27]
	s_waitcnt vmcnt(8)
	s_waitcnt lgkmcnt(0)
	s_barrier
	s_setprio 1
	s_waitcnt lgkmcnt(0)
	v_mfma_f32_16x16x32_bf16 v[126:129], v[148:151], v[180:183], v[126:129]
	v_mfma_f32_16x16x32_bf16 v[122:125], v[156:159], v[180:183], v[122:125]
	v_mfma_f32_16x16x32_bf16 v[110:113], v[148:151], v[188:191], v[110:113]
	v_mfma_f32_16x16x32_bf16 v[106:109], v[156:159], v[188:191], v[106:109]
	v_mfma_f32_16x16x32_bf16 v[94:97], v[148:151], v[208:211], v[94:97]
	v_mfma_f32_16x16x32_bf16 v[90:93], v[156:159], v[208:211], v[90:93]
	v_mfma_f32_16x16x32_bf16 v[78:81], v[148:151], v[216:219], v[78:81]
	v_mfma_f32_16x16x32_bf16 v[74:77], v[156:159], v[216:219], v[74:77]
	v_mfma_f32_16x16x32_bf16 v[126:129], v[152:155], v[184:187], v[126:129]
	v_mfma_f32_16x16x32_bf16 v[122:125], v[160:163], v[184:187], v[122:125]
	v_mfma_f32_16x16x32_bf16 v[110:113], v[152:155], v[204:207], v[110:113]
	v_mfma_f32_16x16x32_bf16 v[106:109], v[160:163], v[204:207], v[106:109]
	v_mfma_f32_16x16x32_bf16 v[94:97], v[152:155], v[212:215], v[94:97]
	v_mfma_f32_16x16x32_bf16 v[90:93], v[160:163], v[212:215], v[90:93]
	v_mfma_f32_16x16x32_bf16 v[78:81], v[152:155], v[220:223], v[78:81]
	v_mfma_f32_16x16x32_bf16 v[74:77], v[160:163], v[220:223], v[74:77]
	v_mfma_f32_16x16x32_bf16 v[118:121], v[164:167], v[180:183], v[118:121]
	v_mfma_f32_16x16x32_bf16 v[114:117], v[172:175], v[180:183], v[114:117]
	v_mfma_f32_16x16x32_bf16 v[102:105], v[164:167], v[188:191], v[102:105]
	v_mfma_f32_16x16x32_bf16 v[98:101], v[172:175], v[188:191], v[98:101]
	v_mfma_f32_16x16x32_bf16 v[86:89], v[164:167], v[208:211], v[86:89]
	v_mfma_f32_16x16x32_bf16 v[82:85], v[172:175], v[208:211], v[82:85]
	v_mfma_f32_16x16x32_bf16 v[70:73], v[164:167], v[216:219], v[70:73]
	v_mfma_f32_16x16x32_bf16 v[66:69], v[172:175], v[216:219], v[66:69]
	v_mfma_f32_16x16x32_bf16 v[118:121], v[168:171], v[184:187], v[118:121]
	v_mfma_f32_16x16x32_bf16 v[114:117], v[176:179], v[184:187], v[114:117]
	v_mfma_f32_16x16x32_bf16 v[102:105], v[168:171], v[204:207], v[102:105]
	v_mfma_f32_16x16x32_bf16 v[98:101], v[176:179], v[204:207], v[98:101]
	v_mfma_f32_16x16x32_bf16 v[86:89], v[168:171], v[212:215], v[86:89]
	v_mfma_f32_16x16x32_bf16 v[82:85], v[176:179], v[212:215], v[82:85]
	v_mfma_f32_16x16x32_bf16 v[70:73], v[168:171], v[220:223], v[70:73]
	v_mfma_f32_16x16x32_bf16 v[66:69], v[176:179], v[220:223], v[66:69]
	s_setprio 0
	s_barrier
	s_add_u32 s26, s24, 0x8000
	s_addc_u32 s27, s25, 0
	s_add_i32 s36, s36, s52
	s_mov_b32 m0, s36
	ds_read_b128 v[180:183], v146 offset:49152
	ds_read_b128 v[184:187], v146 offset:50176
	ds_read_b128 v[188:191], v146 offset:51200
	ds_read_b128 v[204:207], v146 offset:52224
	ds_read_b128 v[208:211], v146 offset:53248
	ds_read_b128 v[212:215], v146 offset:54272
	ds_read_b128 v[216:219], v146 offset:55296
	ds_read_b128 v[220:223], v146 offset:56320
	global_load_lds_dwordx4 v134, s[26:27]
	s_add_i32 m0, s36, 0x2000
	s_add_u32 s24, s24, 0xc000
	s_addc_u32 s25, s25, 0
	global_load_lds_dwordx4 v130, s[26:27]
	s_add_i32 s26, s37, s52
	s_mov_b32 m0, s26
	s_nop 0
	global_load_lds_dwordx4 v134, s[24:25]
	s_add_i32 m0, s26, 0x2000
	s_nop 0
	global_load_lds_dwordx4 v130, s[24:25]
	s_mov_b32 m0, s59
	s_nop 0
	global_load_lds_dwordx4 v136, s[22:23]
	s_mov_b32 m0, s60
	s_nop 0
	global_load_lds_dwordx4 v132, s[22:23]
	s_waitcnt vmcnt(8)
	s_waitcnt lgkmcnt(0)
	s_barrier
	s_setprio 1
	s_waitcnt lgkmcnt(0)
	v_mfma_f32_16x16x32_bf16 v[62:65], v[148:151], v[180:183], v[62:65]
	v_mfma_f32_16x16x32_bf16 v[58:61], v[156:159], v[180:183], v[58:61]
	v_mfma_f32_16x16x32_bf16 v[46:49], v[148:151], v[188:191], v[46:49]
	v_mfma_f32_16x16x32_bf16 v[42:45], v[156:159], v[188:191], v[42:45]
	v_mfma_f32_16x16x32_bf16 v[30:33], v[148:151], v[208:211], v[30:33]
	v_mfma_f32_16x16x32_bf16 v[26:29], v[156:159], v[208:211], v[26:29]
	v_mfma_f32_16x16x32_bf16 v[14:17], v[148:151], v[216:219], v[14:17]
	v_mfma_f32_16x16x32_bf16 v[10:13], v[156:159], v[216:219], v[10:13]
	v_mfma_f32_16x16x32_bf16 v[62:65], v[152:155], v[184:187], v[62:65]
	v_mfma_f32_16x16x32_bf16 v[58:61], v[160:163], v[184:187], v[58:61]
	v_mfma_f32_16x16x32_bf16 v[46:49], v[152:155], v[204:207], v[46:49]
	v_mfma_f32_16x16x32_bf16 v[42:45], v[160:163], v[204:207], v[42:45]
	v_mfma_f32_16x16x32_bf16 v[30:33], v[152:155], v[212:215], v[30:33]
	v_mfma_f32_16x16x32_bf16 v[26:29], v[160:163], v[212:215], v[26:29]
	v_mfma_f32_16x16x32_bf16 v[14:17], v[152:155], v[220:223], v[14:17]
	v_mfma_f32_16x16x32_bf16 v[10:13], v[160:163], v[220:223], v[10:13]
	v_mfma_f32_16x16x32_bf16 v[54:57], v[164:167], v[180:183], v[54:57]
	v_mfma_f32_16x16x32_bf16 v[50:53], v[172:175], v[180:183], v[50:53]
	v_mfma_f32_16x16x32_bf16 v[38:41], v[164:167], v[188:191], v[38:41]
	v_mfma_f32_16x16x32_bf16 v[34:37], v[172:175], v[188:191], v[34:37]
	v_mfma_f32_16x16x32_bf16 v[22:25], v[164:167], v[208:211], v[22:25]
	v_mfma_f32_16x16x32_bf16 v[18:21], v[172:175], v[208:211], v[18:21]
	v_mfma_f32_16x16x32_bf16 v[6:9], v[164:167], v[216:219], v[6:9]
	v_mfma_f32_16x16x32_bf16 v[2:5], v[172:175], v[216:219], v[2:5]
	v_mfma_f32_16x16x32_bf16 v[54:57], v[168:171], v[184:187], v[54:57]
	v_mfma_f32_16x16x32_bf16 v[50:53], v[176:179], v[184:187], v[50:53]
	v_mfma_f32_16x16x32_bf16 v[38:41], v[168:171], v[204:207], v[38:41]
	v_mfma_f32_16x16x32_bf16 v[34:37], v[176:179], v[204:207], v[34:37]
	v_mfma_f32_16x16x32_bf16 v[22:25], v[168:171], v[212:215], v[22:25]
	v_mfma_f32_16x16x32_bf16 v[18:21], v[176:179], v[212:215], v[18:21]
	v_mfma_f32_16x16x32_bf16 v[6:9], v[168:171], v[220:223], v[6:9]
	v_mfma_f32_16x16x32_bf16 v[2:5], v[176:179], v[220:223], v[2:5]
	s_setprio 0
	s_barrier
	s_add_i32 s76, s76, 2
	s_add_u32 s66, s66, 0x10000
	s_addc_u32 s67, s67, 0
	s_add_u32 s20, s20, 0x10000
	s_addc_u32 s21, s21, 0
	s_cmp_gt_u32 s76, 29
	s_cbranch_scc0 .LBB0_1100
	s_and_b64 vcc, exec, s[6:7]
	s_cbranch_vccz .LBB0_1103
	s_barrier

; #define PG8_STAGE(bufoff, gbase, voff) do { _Pragma("unroll") for (int _i = 0; _i < 2; ++_i) \
;         __builtin_amdgcn_global_load_lds((const unsigned*)((const char*)(gbase) + (voff)[_i]), (LAS unsigned*)(lds + (bufoff) + ldsw + _i * 8192), 16, 0, 0); } while (0)
; #define PG8_LDA(dst, b, h) do { _Pragma("unroll") for (int m = 0; m < 4; ++m) _Pragma("unroll") for (int k = 0; k < 2; ++k) dst[m][k] = *(const LAS bf16x8*)(lds + PG8_SA(b, h) + aoff + m * 2048 + k * 1024); } while (0)
; #define PG8_LDB(dst, b, h) do { _Pragma("unroll") for (int n = 0; n < 2; ++n) _Pragma("unroll") for (int k = 0; k < 2; ++k) dst[n][k] = *(const LAS bf16x8*)(lds + PG8_SB(b, h) + boff + n * 2048 + k * 1024); } while (0)
; #define PG8_MMA(ai, bj, At, Bt) do { __builtin_amdgcn_s_setprio(1); _Pragma("unroll") for (int m = 0; m < 4; ++m) _Pragma("unroll") for (int n = 0; n < 2; ++n) _Pragma("unroll") for (int k = 0; k < 2; ++k) \
;         acc[ai][bj][m][n] = __builtin_amdgcn_mfma_f32_16x16x32_bf16(Bt[n][k], At[m][k], acc[ai][bj][m][n], 0, 0, 0); __builtin_amdgcn_s_setprio(0); } while (0)
; #define PG8_WAIT_V(n) asm volatile("s_waitcnt vmcnt(" #n ")" ::: "memory")
; #define PG8_WAIT_L(n) asm volatile("s_waitcnt lgkmcnt(" #n ")" ::: "memory")
; #define PG8_BAR __builtin_amdgcn_s_barrier()
; #define PG8_SCHED __builtin_amdgcn_sched_barrier(0)
; template <class Epi, class Sched>
; __device__ __forceinline__ void gemm_phase(const int tid, LAS unsigned char* lds, const Gemm g, const Sched& S, const Epi& E) {
;     ...
;         for (int t = 0; t < nt; t += 2) {
;             const bool last = (t == nt - 2);
;             const char* a1 = cA + (size_t)(t + 1) * kstepA;
;             const char* a2 = last ? nA : cA + (size_t)(t + 2) * kstepA; const char* b2 = last ? nB : cB + (size_t)(t + 2) * kstepB;
;             const char* a3 = a2 + kstepA; const char* b3 = b2 + kstepB;
;             PG8_LDB(B0, 0, 0); PG8_LDB(B1, 0, 1); PG8_SCHED; PG8_LDA(At, 0, 0); PG8_STAGE(PG8_SA(1, 1), a1 + hstepA, voffA);
;             PG8_WAIT_V(8); PG8_WAIT_L(0); PG8_BAR; PG8_MMA(0, 0, At, B0); PG8_MMA(0, 1, At, B1); PG8_BAR; PG8_SCHED;
;             PG8_LDA(At, 0, 1); PG8_STAGE(PG8_SB(0, 0), b2, voffB); PG8_STAGE(PG8_SB(0, 1), b2 + hstepB, voffB); PG8_STAGE(PG8_SA(0, 0), a2, voffA);
;             PG8_WAIT_V(8); PG8_WAIT_L(0); PG8_BAR; PG8_MMA(1, 0, At, B0); PG8_MMA(1, 1, At, B1); PG8_BAR; PG8_SCHED;
.LBB0_1171:
	s_add_u32 s16, s14, 0x4000
	s_addc_u32 s17, s15, 0
	s_cmpk_eq_i32 s62, 0x54
	s_cselect_b32 s20, s6, s16
	s_cselect_b32 s21, s7, s17
	s_cselect_b32 s18, s12, s60
	s_cselect_b32 s19, s13, s61
	s_add_u32 s16, s20, 0x8000
	s_addc_u32 s17, s21, 0
	s_add_i32 s36, 16, 0x10000
	s_add_i32 s37, 16, 0x14000
	v_add_u32_e32 v148, s36, v157
	v_add_u32_e32 v168, s37, v157
	ds_read_b128 v[130:133], v148
	ds_read_b128 v[134:137], v148 offset:1024
	ds_read_b128 v[138:141], v148 offset:2048
	ds_read_b128 v[148:151], v148 offset:3072
	ds_read_b128 v[152:155], v168
	ds_read_b128 v[160:163], v168 offset:1024
	ds_read_b128 v[164:167], v168 offset:2048
	ds_read_b128 v[168:171], v168 offset:3072
	s_add_i32 m0, s30, 0xc000
	ds_read_b128 v[172:175], v159
	ds_read_b128 v[176:179], v159 offset:1024
	ds_read_b128 v[180:183], v159 offset:2048
	ds_read_b128 v[184:187], v159 offset:3072
	ds_read_b128 v[188:191], v159 offset:4096
	ds_read_b128 v[204:207], v159 offset:5120
	ds_read_b128 v[208:211], v159 offset:6144
	ds_read_b128 v[212:215], v159 offset:7168
	global_load_lds_dwordx4 v146, s[14:15]
	s_add_i32 m0, s30, 0xe000
	s_nop 0
	global_load_lds_dwordx4 v144, s[14:15]
	s_waitcnt vmcnt(8)
	s_waitcnt lgkmcnt(0)
	s_barrier
	s_setprio 1
	s_waitcnt lgkmcnt(0)
	v_mfma_f32_16x16x32_bf16 v[126:129], v[130:133], v[172:175], v[126:129]
	v_mfma_f32_16x16x32_bf16 v[122:125], v[138:141], v[172:175], v[122:125]
	v_mfma_f32_16x16x32_bf16 v[118:121], v[130:133], v[180:183], v[118:121]
	v_mfma_f32_16x16x32_bf16 v[106:109], v[138:141], v[180:183], v[106:109]
	v_mfma_f32_16x16x32_bf16 v[102:105], v[130:133], v[188:191], v[102:105]
	v_mfma_f32_16x16x32_bf16 v[90:93], v[138:141], v[188:191], v[90:93]
	v_mfma_f32_16x16x32_bf16 v[86:89], v[130:133], v[208:211], v[86:89]
	v_mfma_f32_16x16x32_bf16 v[74:77], v[138:141], v[208:211], v[74:77]
	v_mfma_f32_16x16x32_bf16 v[126:129], v[134:137], v[176:179], v[126:129]
	v_mfma_f32_16x16x32_bf16 v[122:125], v[148:151], v[176:179], v[122:125]
	v_mfma_f32_16x16x32_bf16 v[118:121], v[134:137], v[184:187], v[118:121]
	v_mfma_f32_16x16x32_bf16 v[106:109], v[148:151], v[184:187], v[106:109]
	v_mfma_f32_16x16x32_bf16 v[102:105], v[134:137], v[204:207], v[102:105]
	v_mfma_f32_16x16x32_bf16 v[90:93], v[148:151], v[204:207], v[90:93]
	v_mfma_f32_16x16x32_bf16 v[86:89], v[134:137], v[212:215], v[86:89]
	v_mfma_f32_16x16x32_bf16 v[74:77], v[148:151], v[212:215], v[74:77]
	v_mfma_f32_16x16x32_bf16 v[114:117], v[152:155], v[172:175], v[114:117]
	v_mfma_f32_16x16x32_bf16 v[110:113], v[164:167], v[172:175], v[110:113]
	v_mfma_f32_16x16x32_bf16 v[98:101], v[152:155], v[180:183], v[98:101]
	v_mfma_f32_16x16x32_bf16 v[94:97], v[164:167], v[180:183], v[94:97]
	v_mfma_f32_16x16x32_bf16 v[82:85], v[152:155], v[188:191], v[82:85]
	v_mfma_f32_16x16x32_bf16 v[78:81], v[164:167], v[188:191], v[78:81]
	v_mfma_f32_16x16x32_bf16 v[70:73], v[152:155], v[208:211], v[70:73]
	v_mfma_f32_16x16x32_bf16 v[66:69], v[164:167], v[208:211], v[66:69]
	v_mfma_f32_16x16x32_bf16 v[114:117], v[160:163], v[176:179], v[114:117]
	v_mfma_f32_16x16x32_bf16 v[110:113], v[168:171], v[176:179], v[110:113]
	v_mfma_f32_16x16x32_bf16 v[98:101], v[160:163], v[184:187], v[98:101]
	v_mfma_f32_16x16x32_bf16 v[94:97], v[168:171], v[184:187], v[94:97]
	v_mfma_f32_16x16x32_bf16 v[82:85], v[160:163], v[204:207], v[82:85]
	v_mfma_f32_16x16x32_bf16 v[78:81], v[168:171], v[204:207], v[78:81]
	v_mfma_f32_16x16x32_bf16 v[70:73], v[160:163], v[212:215], v[70:73]
	v_mfma_f32_16x16x32_bf16 v[66:69], v[168:171], v[212:215], v[66:69]
	s_setprio 0
	s_barrier
	s_add_i32 s36, s36, s29
	s_mov_b32 m0, s36
	ds_read_b128 v[172:175], v159 offset:16384
	ds_read_b128 v[176:179], v159 offset:17408
	ds_read_b128 v[180:183], v159 offset:18432
	ds_read_b128 v[184:187], v159 offset:19456
	ds_read_b128 v[188:191], v159 offset:20480
	ds_read_b128 v[204:207], v159 offset:21504
	ds_read_b128 v[208:211], v159 offset:22528
	ds_read_b128 v[212:215], v159 offset:23552
	global_load_lds_dwordx4 v0, s[18:19]
	s_add_i32 m0, s36, 0x2000
	s_add_u32 s64, s18, 0x4000
	s_addc_u32 s65, s19, 0
	s_add_i32 s36, s37, s29
	global_load_lds_dwordx4 v142, s[18:19]
	s_mov_b32 m0, s36
	s_nop 0
	global_load_lds_dwordx4 v0, s[64:65]
	s_add_i32 m0, s36, 0x2000
	s_nop 0
	global_load_lds_dwordx4 v142, s[64:65]
	s_mov_b32 m0, s30
	s_nop 0
	global_load_lds_dwordx4 v0, s[20:21]
	s_mov_b32 m0, s31
	s_nop 0
	global_load_lds_dwordx4 v142, s[20:21]
	s_waitcnt vmcnt(8)
	s_waitcnt lgkmcnt(0)
	s_barrier
	s_setprio 1
	s_waitcnt lgkmcnt(0)
	v_mfma_f32_16x16x32_bf16 v[62:65], v[130:133], v[172:175], v[62:65]
	v_mfma_f32_16x16x32_bf16 v[58:61], v[138:141], v[172:175], v[58:61]
	v_mfma_f32_16x16x32_bf16 v[54:57], v[130:133], v[180:183], v[54:57]
	v_mfma_f32_16x16x32_bf16 v[42:45], v[138:141], v[180:183], v[42:45]
	v_mfma_f32_16x16x32_bf16 v[38:41], v[130:133], v[188:191], v[38:41]
	v_mfma_f32_16x16x32_bf16 v[26:29], v[138:141], v[188:191], v[26:29]
	v_mfma_f32_16x16x32_bf16 v[22:25], v[130:133], v[208:211], v[22:25]
	v_mfma_f32_16x16x32_bf16 v[10:13], v[138:141], v[208:211], v[10:13]
	v_mfma_f32_16x16x32_bf16 v[62:65], v[134:137], v[176:179], v[62:65]
	v_mfma_f32_16x16x32_bf16 v[58:61], v[148:151], v[176:179], v[58:61]
	v_mfma_f32_16x16x32_bf16 v[54:57], v[134:137], v[184:187], v[54:57]
	v_mfma_f32_16x16x32_bf16 v[42:45], v[148:151], v[184:187], v[42:45]
	v_mfma_f32_16x16x32_bf16 v[38:41], v[134:137], v[204:207], v[38:41]
	v_mfma_f32_16x16x32_bf16 v[26:29], v[148:151], v[204:207], v[26:29]
	v_mfma_f32_16x16x32_bf16 v[22:25], v[134:137], v[212:215], v[22:25]
	v_mfma_f32_16x16x32_bf16 v[10:13], v[148:151], v[212:215], v[10:13]
	v_mfma_f32_16x16x32_bf16 v[50:53], v[152:155], v[172:175], v[50:53]
	v_mfma_f32_16x16x32_bf16 v[46:49], v[164:167], v[172:175], v[46:49]
	v_mfma_f32_16x16x32_bf16 v[34:37], v[152:155], v[180:183], v[34:37]
	v_mfma_f32_16x16x32_bf16 v[30:33], v[164:167], v[180:183], v[30:33]
	v_mfma_f32_16x16x32_bf16 v[18:21], v[152:155], v[188:191], v[18:21]
	v_mfma_f32_16x16x32_bf16 v[14:17], v[164:167], v[188:191], v[14:17]
	v_mfma_f32_16x16x32_bf16 v[6:9], v[152:155], v[208:211], v[6:9]
	v_mfma_f32_16x16x32_bf16 v[2:5], v[164:167], v[208:211], v[2:5]
	v_mfma_f32_16x16x32_bf16 v[50:53], v[160:163], v[176:179], v[50:53]
	v_mfma_f32_16x16x32_bf16 v[46:49], v[168:171], v[176:179], v[46:49]
	v_mfma_f32_16x16x32_bf16 v[34:37], v[160:163], v[184:187], v[34:37]
	v_mfma_f32_16x16x32_bf16 v[30:33], v[168:171], v[184:187], v[30:33]
	v_mfma_f32_16x16x32_bf16 v[18:21], v[160:163], v[204:207], v[18:21]
	v_mfma_f32_16x16x32_bf16 v[14:17], v[168:171], v[204:207], v[14:17]
	v_mfma_f32_16x16x32_bf16 v[6:9], v[160:163], v[212:215], v[6:9]
	v_mfma_f32_16x16x32_bf16 v[2:5], v[168:171], v[212:215], v[2:5]
	s_setprio 0
	s_barrier
; #define PG8_STAGE(bufoff, gbase, voff) do { _Pragma("unroll") for (int _i = 0; _i < 2; ++_i) \
;         __builtin_amdgcn_global_load_lds((const unsigned*)((const char*)(gbase) + (voff)[_i]), (LAS unsigned*)(lds + (bufoff) + ldsw + _i * 8192), 16, 0, 0); } while (0)
; #define PG8_LDA(dst, b, h) do { _Pragma("unroll") for (int m = 0; m < 4; ++m) _Pragma("unroll") for (int k = 0; k < 2; ++k) dst[m][k] = *(const LAS bf16x8*)(lds + PG8_SA(b, h) + aoff + m * 2048 + k * 1024); } while (0)
; #define PG8_LDB(dst, b, h) do { _Pragma("unroll") for (int n = 0; n < 2; ++n) _Pragma("unroll") for (int k = 0; k < 2; ++k) dst[n][k] = *(const LAS bf16x8*)(lds + PG8_SB(b, h) + boff + n * 2048 + k * 1024); } while (0)
; #define PG8_MMA(ai, bj, At, Bt) do { __builtin_amdgcn_s_setprio(1); _Pragma("unroll") for (int m = 0; m < 4; ++m) _Pragma("unroll") for (int n = 0; n < 2; ++n) _Pragma("unroll") for (int k = 0; k < 2; ++k) \
;         acc[ai][bj][m][n] = __builtin_amdgcn_mfma_f32_16x16x32_bf16(Bt[n][k], At[m][k], acc[ai][bj][m][n], 0, 0, 0); __builtin_amdgcn_s_setprio(0); } while (0)
; #define PG8_WAIT_V(n) asm volatile("s_waitcnt vmcnt(" #n ")" ::: "memory")
; #define PG8_WAIT_L(n) asm volatile("s_waitcnt lgkmcnt(" #n ")" ::: "memory")
; #define PG8_BAR __builtin_amdgcn_s_barrier()
; #define PG8_SCHED __builtin_amdgcn_sched_barrier(0)
; template <class Epi, class Sched>
; __device__ __forceinline__ void gemm_phase(const int tid, LAS unsigned char* lds, const Gemm g, const Sched& S, const Epi& E) {
;     ...
;             PG8_LDB(B0, 1, 0); PG8_LDB(B1, 1, 1); PG8_SCHED; PG8_LDA(At, 1, 0); PG8_STAGE(PG8_SA(0, 1), a2 + hstepA, voffA);
;             PG8_WAIT_V(8); PG8_WAIT_L(0); PG8_BAR; PG8_MMA(0, 0, At, B0); PG8_MMA(0, 1, At, B1); PG8_BAR; PG8_SCHED;
;             PG8_LDA(At, 1, 1); PG8_STAGE(PG8_SB(1, 0), b3, voffB); PG8_STAGE(PG8_SB(1, 1), b3 + hstepB, voffB); PG8_STAGE(PG8_SA(1, 0), a3, voffA);
;             PG8_WAIT_V(8); PG8_WAIT_L(0); PG8_BAR; PG8_MMA(1, 0, At, B0); PG8_MMA(1, 1, At, B1); PG8_BAR; PG8_SCHED;
;         }
;         if (wr == 0) PG8_BAR;
	s_add_i32 s36, 16, 0x18000
	s_add_i32 s37, 16, 0x1c000
	v_add_u32_e32 v148, s36, v157
	v_add_u32_e32 v168, s37, v157
	ds_read_b128 v[130:133], v148
	ds_read_b128 v[134:137], v148 offset:1024
	ds_read_b128 v[138:141], v148 offset:2048
	ds_read_b128 v[148:151], v148 offset:3072
	ds_read_b128 v[152:155], v168
	ds_read_b128 v[160:163], v168 offset:1024
	ds_read_b128 v[164:167], v168 offset:2048
	ds_read_b128 v[168:171], v168 offset:3072
	s_add_u32 s20, s20, 0x4000
	s_addc_u32 s21, s21, 0
	s_mov_b32 m0, s34
	ds_read_b128 v[172:175], v159 offset:32768
	ds_read_b128 v[176:179], v159 offset:33792
	ds_read_b128 v[180:183], v159 offset:34816
	ds_read_b128 v[184:187], v159 offset:35840
	ds_read_b128 v[188:191], v159 offset:36864
	ds_read_b128 v[204:207], v159 offset:37888
	ds_read_b128 v[208:211], v159 offset:38912
	ds_read_b128 v[212:215], v159 offset:39936
	global_load_lds_dwordx4 v0, s[20:21]
	s_mov_b32 m0, s35
	s_nop 0
	global_load_lds_dwordx4 v142, s[20:21]
	s_waitcnt vmcnt(8)
	s_waitcnt lgkmcnt(0)
	s_barrier
	s_setprio 1
	s_waitcnt lgkmcnt(0)
	v_mfma_f32_16x16x32_bf16 v[126:129], v[130:133], v[172:175], v[126:129]
	v_mfma_f32_16x16x32_bf16 v[122:125], v[138:141], v[172:175], v[122:125]
	v_mfma_f32_16x16x32_bf16 v[118:121], v[130:133], v[180:183], v[118:121]
	v_mfma_f32_16x16x32_bf16 v[106:109], v[138:141], v[180:183], v[106:109]
	v_mfma_f32_16x16x32_bf16 v[102:105], v[130:133], v[188:191], v[102:105]
	v_mfma_f32_16x16x32_bf16 v[90:93], v[138:141], v[188:191], v[90:93]
	v_mfma_f32_16x16x32_bf16 v[86:89], v[130:133], v[208:211], v[86:89]
	v_mfma_f32_16x16x32_bf16 v[74:77], v[138:141], v[208:211], v[74:77]
	v_mfma_f32_16x16x32_bf16 v[126:129], v[134:137], v[176:179], v[126:129]
	v_mfma_f32_16x16x32_bf16 v[122:125], v[148:151], v[176:179], v[122:125]
	v_mfma_f32_16x16x32_bf16 v[118:121], v[134:137], v[184:187], v[118:121]
	v_mfma_f32_16x16x32_bf16 v[106:109], v[148:151], v[184:187], v[106:109]
	v_mfma_f32_16x16x32_bf16 v[102:105], v[134:137], v[204:207], v[102:105]
	v_mfma_f32_16x16x32_bf16 v[90:93], v[148:151], v[204:207], v[90:93]
	v_mfma_f32_16x16x32_bf16 v[86:89], v[134:137], v[212:215], v[86:89]
	v_mfma_f32_16x16x32_bf16 v[74:77], v[148:151], v[212:215], v[74:77]
	v_mfma_f32_16x16x32_bf16 v[114:117], v[152:155], v[172:175], v[114:117]
	v_mfma_f32_16x16x32_bf16 v[110:113], v[164:167], v[172:175], v[110:113]
	v_mfma_f32_16x16x32_bf16 v[98:101], v[152:155], v[180:183], v[98:101]
	v_mfma_f32_16x16x32_bf16 v[94:97], v[164:167], v[180:183], v[94:97]
	v_mfma_f32_16x16x32_bf16 v[82:85], v[152:155], v[188:191], v[82:85]
	v_mfma_f32_16x16x32_bf16 v[78:81], v[164:167], v[188:191], v[78:81]
	v_mfma_f32_16x16x32_bf16 v[70:73], v[152:155], v[208:211], v[70:73]
	v_mfma_f32_16x16x32_bf16 v[66:69], v[164:167], v[208:211], v[66:69]
	v_mfma_f32_16x16x32_bf16 v[114:117], v[160:163], v[176:179], v[114:117]
	v_mfma_f32_16x16x32_bf16 v[110:113], v[168:171], v[176:179], v[110:113]
	v_mfma_f32_16x16x32_bf16 v[98:101], v[160:163], v[184:187], v[98:101]
	v_mfma_f32_16x16x32_bf16 v[94:97], v[168:171], v[184:187], v[94:97]
	v_mfma_f32_16x16x32_bf16 v[82:85], v[160:163], v[204:207], v[82:85]
	v_mfma_f32_16x16x32_bf16 v[78:81], v[168:171], v[204:207], v[78:81]
	v_mfma_f32_16x16x32_bf16 v[70:73], v[160:163], v[212:215], v[70:73]
	v_mfma_f32_16x16x32_bf16 v[66:69], v[168:171], v[212:215], v[66:69]
	s_setprio 0
	s_barrier
	s_add_u32 s20, s18, 0x8000
	s_addc_u32 s21, s19, 0
	s_add_i32 s36, s36, s29
	s_mov_b32 m0, s36
	ds_read_b128 v[172:175], v159 offset:49152
	ds_read_b128 v[176:179], v159 offset:50176
	ds_read_b128 v[180:183], v159 offset:51200
	ds_read_b128 v[184:187], v159 offset:52224
	ds_read_b128 v[188:191], v159 offset:53248
	ds_read_b128 v[204:207], v159 offset:54272
	ds_read_b128 v[208:211], v159 offset:55296
	ds_read_b128 v[212:215], v159 offset:56320
	global_load_lds_dwordx4 v0, s[20:21]
	s_add_i32 m0, s36, 0x2000
	s_add_u32 s18, s18, 0xc000
	s_addc_u32 s19, s19, 0
	global_load_lds_dwordx4 v142, s[20:21]
	s_add_i32 s20, s37, s29
	s_mov_b32 m0, s20
	s_nop 0
	global_load_lds_dwordx4 v0, s[18:19]
	s_add_i32 m0, s20, 0x2000
	s_nop 0
	global_load_lds_dwordx4 v142, s[18:19]
	s_mov_b32 m0, s53
	s_nop 0
	global_load_lds_dwordx4 v0, s[16:17]
	s_mov_b32 m0, s54
	s_nop 0
	global_load_lds_dwordx4 v142, s[16:17]
	s_waitcnt vmcnt(8)
	s_waitcnt lgkmcnt(0)
	s_barrier
	s_setprio 1
	s_waitcnt lgkmcnt(0)
	v_mfma_f32_16x16x32_bf16 v[62:65], v[130:133], v[172:175], v[62:65]
	v_mfma_f32_16x16x32_bf16 v[58:61], v[138:141], v[172:175], v[58:61]
	v_mfma_f32_16x16x32_bf16 v[54:57], v[130:133], v[180:183], v[54:57]
	v_mfma_f32_16x16x32_bf16 v[42:45], v[138:141], v[180:183], v[42:45]
	v_mfma_f32_16x16x32_bf16 v[38:41], v[130:133], v[188:191], v[38:41]
	v_mfma_f32_16x16x32_bf16 v[26:29], v[138:141], v[188:191], v[26:29]
	v_mfma_f32_16x16x32_bf16 v[22:25], v[130:133], v[208:211], v[22:25]
	v_mfma_f32_16x16x32_bf16 v[10:13], v[138:141], v[208:211], v[10:13]
	v_mfma_f32_16x16x32_bf16 v[62:65], v[134:137], v[176:179], v[62:65]
	v_mfma_f32_16x16x32_bf16 v[58:61], v[148:151], v[176:179], v[58:61]
	v_mfma_f32_16x16x32_bf16 v[54:57], v[134:137], v[184:187], v[54:57]
	v_mfma_f32_16x16x32_bf16 v[42:45], v[148:151], v[184:187], v[42:45]
	v_mfma_f32_16x16x32_bf16 v[38:41], v[134:137], v[204:207], v[38:41]
	v_mfma_f32_16x16x32_bf16 v[26:29], v[148:151], v[204:207], v[26:29]
	v_mfma_f32_16x16x32_bf16 v[22:25], v[134:137], v[212:215], v[22:25]
	v_mfma_f32_16x16x32_bf16 v[10:13], v[148:151], v[212:215], v[10:13]
	v_mfma_f32_16x16x32_bf16 v[50:53], v[152:155], v[172:175], v[50:53]
	v_mfma_f32_16x16x32_bf16 v[46:49], v[164:167], v[172:175], v[46:49]
	v_mfma_f32_16x16x32_bf16 v[34:37], v[152:155], v[180:183], v[34:37]
	v_mfma_f32_16x16x32_bf16 v[30:33], v[164:167], v[180:183], v[30:33]
	v_mfma_f32_16x16x32_bf16 v[18:21], v[152:155], v[188:191], v[18:21]
	v_mfma_f32_16x16x32_bf16 v[14:17], v[164:167], v[188:191], v[14:17]
	v_mfma_f32_16x16x32_bf16 v[6:9], v[152:155], v[208:211], v[6:9]
	v_mfma_f32_16x16x32_bf16 v[2:5], v[164:167], v[208:211], v[2:5]
	v_mfma_f32_16x16x32_bf16 v[50:53], v[160:163], v[176:179], v[50:53]
	v_mfma_f32_16x16x32_bf16 v[46:49], v[168:171], v[176:179], v[46:49]
	v_mfma_f32_16x16x32_bf16 v[34:37], v[160:163], v[184:187], v[34:37]
	v_mfma_f32_16x16x32_bf16 v[30:33], v[168:171], v[184:187], v[30:33]
	v_mfma_f32_16x16x32_bf16 v[18:21], v[160:163], v[204:207], v[18:21]
	v_mfma_f32_16x16x32_bf16 v[14:17], v[168:171], v[204:207], v[14:17]
	v_mfma_f32_16x16x32_bf16 v[6:9], v[160:163], v[212:215], v[6:9]
	v_mfma_f32_16x16x32_bf16 v[2:5], v[168:171], v[212:215], v[2:5]
	s_setprio 0
	s_barrier
	s_add_i32 s62, s62, 2
	s_add_u32 s60, s60, 0x10000
	s_addc_u32 s61, s61, 0
	s_add_u32 s14, s14, 0x10000
	s_addc_u32 s15, s15, 0
	s_cmpk_gt_u32 s62, 0x55
	s_cbranch_scc0 .LBB0_1171
	s_and_b64 vcc, exec, s[10:11]
	s_cbranch_vccz .LBB0_1174
	s_barrier
